# speedup vs baseline: 1.0030x; 1.0030x over previous
; #define PG8_STAGE(bufoff, gbase, voff) do { _Pragma("unroll") for (int _i = 0; _i < 2; ++_i) \
;         __builtin_amdgcn_global_load_lds((const unsigned*)((const char*)(gbase) + (voff)[_i]), (LAS unsigned*)(lds + (bufoff) + ldsw + _i * 8192), 16, 0, 0); } while (0)
; #define PG8_LDA(dst, b, h) do { _Pragma("unroll") for (int m = 0; m < 4; ++m) _Pragma("unroll") for (int k = 0; k < 2; ++k) dst[m][k] = *(const LAS bf16x8*)(lds + PG8_SA(b, h) + aoff + m * 2048 + k * 1024); } while (0)
; #define PG8_LDB(dst, b, h) do { _Pragma("unroll") for (int n = 0; n < 2; ++n) _Pragma("unroll") for (int k = 0; k < 2; ++k) dst[n][k] = *(const LAS bf16x8*)(lds + PG8_SB(b, h) + boff + n * 2048 + k * 1024); } while (0)
; #define PG8_WAIT_L(n) asm volatile("s_waitcnt lgkmcnt(" #n ")" ::: "memory")
; #define PG8_BAR __builtin_amdgcn_s_barrier()
; #define PG8_SCHED __builtin_amdgcn_sched_barrier(0)
; template <class Epi>
; DEV void gemm_phase(LAS unsigned char* lds, const Gemm g, const StaticOrder& S, const Epi& E) {
;     ...
;         const char* nA = has_next ? (const char*)g.A + (size_t)nxt.pm * tstep : cA; const char* nB = has_next ? (const char*)g.Bt + (size_t)nxt.pn * tstep : cB;
;         for (int t = 0; t < nt; t += 2) {
;             const bool last = (t == nt - 2);
;             const char* a1 = cA + (size_t)(t + 1) * kstep;
;             const char* a2 = last ? nA : cA + (size_t)(t + 2) * kstep; const char* b2 = last ? nB : cB + (size_t)(t + 2) * kstep;
;             const char* a3 = a2 + kstep; const char* b3 = b2 + kstep;
;             PG8_LDB(B0, 0, 0); PG8_SCHED; PG8_LDA(At, 0, 0); PG8_STAGE(PG8_SA(1, 1), a1 + hstep, voffA);
;             PG8_WAIT_L(8); PG8_BAR; PG8_WAIT_L(0); PG8_MMA(0, 0, At, B0); PG8_BAR; PG8_SCHED;
;             PG8_LDB(B1, 0, 1); PG8_STAGE(PG8_SB(0, 0), b2, voffB);
;             PG8_BAR; PG8_WAIT_L(0); PG8_MMA(0, 1, At, B1); PG8_BAR;
;     ...
; #pragma unroll
;         for (int a = 0; a < 2; ++a)
; #pragma unroll
;             for (int b = 0; b < 2; ++b)
; #pragma unroll
;                 for (int m = 0; m < 4; ++m)
; #pragma unroll
;                     for (int n = 0; n < 2; ++n) acc[a][b][m][n] = (f32x4){0.f, 0.f, 0.f, 0.f};
;         cur = nxt; cA = nA; cB = nB; ++ui;
.LBB0_587:
	v_mov_b64_e32 v[0:1], 0x4a0
	s_ashr_i32 s9, s8, 31
	v_cmp_lt_i64_e32 vcc, s[10:11], v[0:1]
	s_lshl_b64 s[10:11], s[8:9], 20
	v_readlane_b32 s12, v250, 9
	v_readlane_b32 s13, v250, 10
	s_add_u32 s10, s12, s10
	s_addc_u32 s11, s13, s11
	s_and_b64 s[12:13], vcc, exec
	s_cselect_b32 s1, s11, s15
	s_cselect_b32 s9, s10, s14
	s_ashr_i32 s7, s6, 31
	s_lshl_b64 s[12:13], s[6:7], 20
	v_readlane_b32 s18, v251, 41
	v_readlane_b32 s19, v251, 42
	s_add_u32 s12, s18, s12
	s_addc_u32 s13, s19, s13
	s_and_b64 s[18:19], vcc, exec
	s_cselect_b32 s7, s13, s17
	s_cselect_b32 s35, s12, s16
	s_add_u32 s14, s14, 0x80080
	s_addc_u32 s15, s15, 0
	s_add_u32 s36, s16, 0x100
	s_addc_u32 s37, s17, 0
	s_mov_b32 s40, -2
	v_mov_b64_e32 v[0:1], 0
	v_mov_b64_e32 v[2:3], 0
	v_mov_b64_e32 v[4:5], 0
	v_mov_b64_e32 v[6:7], 0
	v_mov_b64_e32 v[8:9], 0
	v_mov_b64_e32 v[10:11], 0
	v_mov_b64_e32 v[12:13], 0
	v_mov_b64_e32 v[14:15], 0
	v_mov_b64_e32 v[16:17], 0
	v_mov_b64_e32 v[18:19], 0
	v_mov_b64_e32 v[20:21], 0
	v_mov_b64_e32 v[22:23], 0
	v_mov_b64_e32 v[24:25], 0
	v_mov_b64_e32 v[26:27], 0
	v_mov_b64_e32 v[28:29], 0
	v_mov_b64_e32 v[30:31], 0
	v_mov_b64_e32 v[32:33], 0
	v_mov_b64_e32 v[34:35], 0
	v_mov_b64_e32 v[36:37], 0
	v_mov_b64_e32 v[38:39], 0
	v_mov_b64_e32 v[40:41], 0
	v_mov_b64_e32 v[42:43], 0
	v_mov_b64_e32 v[44:45], 0
	v_mov_b64_e32 v[46:47], 0
	v_mov_b64_e32 v[48:49], 0
	v_mov_b64_e32 v[50:51], 0
	v_mov_b64_e32 v[52:53], 0
	v_mov_b64_e32 v[54:55], 0
	v_mov_b64_e32 v[56:57], 0
	v_mov_b64_e32 v[58:59], 0
	v_mov_b64_e32 v[60:61], 0
	v_mov_b64_e32 v[62:63], 0
	v_mov_b64_e32 v[64:65], 0
	v_mov_b64_e32 v[66:67], 0
	v_mov_b64_e32 v[68:69], 0
	v_mov_b64_e32 v[70:71], 0
	v_mov_b64_e32 v[72:73], 0
	v_mov_b64_e32 v[74:75], 0
	v_mov_b64_e32 v[76:77], 0
	v_mov_b64_e32 v[78:79], 0
	v_mov_b64_e32 v[80:81], 0
	v_mov_b64_e32 v[82:83], 0
	v_mov_b64_e32 v[84:85], 0
	v_mov_b64_e32 v[86:87], 0
	v_mov_b64_e32 v[88:89], 0
	v_mov_b64_e32 v[90:91], 0
	v_mov_b64_e32 v[92:93], 0
	v_mov_b64_e32 v[94:95], 0
	v_mov_b64_e32 v[96:97], 0
	v_mov_b64_e32 v[98:99], 0
	v_mov_b64_e32 v[100:101], 0
	v_mov_b64_e32 v[102:103], 0
	v_mov_b64_e32 v[104:105], 0
	v_mov_b64_e32 v[106:107], 0
	v_mov_b64_e32 v[108:109], 0
	v_mov_b64_e32 v[110:111], 0
	v_mov_b64_e32 v[112:113], 0
	v_mov_b64_e32 v[114:115], 0
	v_mov_b64_e32 v[116:117], 0
	v_mov_b64_e32 v[118:119], 0
	v_mov_b64_e32 v[120:121], 0
	v_mov_b64_e32 v[122:123], 0
	v_mov_b64_e32 v[124:125], 0
	v_mov_b64_e32 v[126:127], 0
	v_add_u32_e32 v156, 0x10000, v167
.LBB0_588:
	s_add_u32 s16, s14, 0xfff80080
	s_addc_u32 s17, s15, -1
	s_add_i32 s41, 0, 0x10000
	ds_read_b128 v[128:131], v156
	ds_read_b128 v[132:135], v156 offset:1024
	ds_read_b128 v[150:153], v156 offset:2048
	ds_read_b128 v[174:177], v156 offset:3072
	s_cmp_eq_u32 s40, 28
	s_cselect_b32 s19, s1, s17
	s_cselect_b32 s18, s9, s16
	s_cselect_b32 s17, s7, s37
	s_cselect_b32 s16, s35, s36
	s_add_i32 m0, s24, 0xc000
	ds_read_b128 v[182:185], v219
	ds_read_b128 v[190:193], v219 offset:1024
	ds_read_b128 v[194:197], v219 offset:2048
	ds_read_b128 v[220:223], v219 offset:3072
	ds_read_b128 v[224:227], v219 offset:4096
	ds_read_b128 v[228:231], v219 offset:5120
	ds_read_b128 v[232:235], v219 offset:6144
	ds_read_b128 v[236:239], v219 offset:7168
	global_load_lds_dwordx4 v146, s[14:15]
	s_add_i32 m0, s24, 0xe000
	s_nop 0
	global_load_lds_dwordx4 v148, s[14:15]
	s_waitcnt lgkmcnt(8)
	s_barrier
	s_waitcnt lgkmcnt(0)
	v_mfma_f32_16x16x32_bf16 v[124:127], v[128:131], v[182:185], v[124:127]
	v_mfma_f32_16x16x32_bf16 v[120:123], v[150:153], v[182:185], v[120:123]
	v_mfma_f32_16x16x32_bf16 v[108:111], v[128:131], v[194:197], v[108:111]
	v_mfma_f32_16x16x32_bf16 v[104:107], v[150:153], v[194:197], v[104:107]
	v_mfma_f32_16x16x32_bf16 v[92:95], v[128:131], v[224:227], v[92:95]
	v_mfma_f32_16x16x32_bf16 v[88:91], v[150:153], v[224:227], v[88:91]
	v_mfma_f32_16x16x32_bf16 v[76:79], v[128:131], v[232:235], v[76:79]
	v_mfma_f32_16x16x32_bf16 v[72:75], v[150:153], v[232:235], v[72:75]
	v_mfma_f32_16x16x32_bf16 v[124:127], v[132:135], v[190:193], v[124:127]
	v_mfma_f32_16x16x32_bf16 v[120:123], v[174:177], v[190:193], v[120:123]
	v_mfma_f32_16x16x32_bf16 v[108:111], v[132:135], v[220:223], v[108:111]
	v_mfma_f32_16x16x32_bf16 v[104:107], v[174:177], v[220:223], v[104:107]
	v_mfma_f32_16x16x32_bf16 v[92:95], v[132:135], v[228:231], v[92:95]
	v_mfma_f32_16x16x32_bf16 v[88:91], v[174:177], v[228:231], v[88:91]
	v_mfma_f32_16x16x32_bf16 v[76:79], v[132:135], v[236:239], v[76:79]
	v_mfma_f32_16x16x32_bf16 v[72:75], v[174:177], v[236:239], v[72:75]
	s_barrier
	s_add_i32 s44, 0, 0x14000
	s_add_i32 s41, s41, s22
	ds_read_b128 v[240:243], v156 offset:16384
	ds_read_b128 v[244:247], v156 offset:17408
	ds_read_b128 v[186:189], v156 offset:18432
	ds_read_b128 v[214:217], v156 offset:19456
	v_lshl_add_u64 v[154:155], s[16:17], 0, v[140:141]
	s_mov_b32 m0, s41
	v_lshl_add_u64 v[158:159], s[16:17], 0, v[136:137]
	global_load_lds_dwordx4 v140, s[16:17]
	s_add_i32 m0, s41, 0x2000
	s_nop 0
	global_load_lds_dwordx4 v136, s[16:17]
	s_barrier
; #define PG8_STAGE(bufoff, gbase, voff) do { _Pragma("unroll") for (int _i = 0; _i < 2; ++_i) \
;         __builtin_amdgcn_global_load_lds((const unsigned*)((const char*)(gbase) + (voff)[_i]), (LAS unsigned*)(lds + (bufoff) + ldsw + _i * 8192), 16, 0, 0); } while (0)
; #define PG8_LDA(dst, b, h) do { _Pragma("unroll") for (int m = 0; m < 4; ++m) _Pragma("unroll") for (int k = 0; k < 2; ++k) dst[m][k] = *(const LAS bf16x8*)(lds + PG8_SA(b, h) + aoff + m * 2048 + k * 1024); } while (0)
; #define PG8_LDB(dst, b, h) do { _Pragma("unroll") for (int n = 0; n < 2; ++n) _Pragma("unroll") for (int k = 0; k < 2; ++k) dst[n][k] = *(const LAS bf16x8*)(lds + PG8_SB(b, h) + boff + n * 2048 + k * 1024); } while (0)
; #define PG8_MMA(ai, bj, At, Bt) do { __builtin_amdgcn_s_setprio(1); _Pragma("unroll") for (int m = 0; m < 4; ++m) _Pragma("unroll") for (int n = 0; n < 2; ++n) _Pragma("unroll") for (int k = 0; k < 2; ++k) \
;         acc[ai][bj][m][n] = __builtin_amdgcn_mfma_f32_16x16x32_bf16(Bt[n][k], At[m][k], acc[ai][bj][m][n], 0, 0, 0); __builtin_amdgcn_s_setprio(0); } while (0)
; #define PG8_WAIT_V(n) asm volatile("s_waitcnt vmcnt(" #n ")" ::: "memory")
; #define PG8_WAIT_L(n) asm volatile("s_waitcnt lgkmcnt(" #n ")" ::: "memory")
; #define PG8_BAR __builtin_amdgcn_s_barrier()
; #define PG8_SCHED __builtin_amdgcn_sched_barrier(0)
; template <class Epi>
; DEV void gemm_phase(LAS unsigned char* lds, const Gemm g, const StaticOrder& S, const Epi& E) {
;     ...
;             PG8_WAIT_L(8); PG8_BAR; PG8_WAIT_L(0); PG8_MMA(0, 0, At, B0); PG8_BAR; PG8_SCHED;
;             PG8_LDB(B1, 0, 1); PG8_STAGE(PG8_SB(0, 0), b2, voffB);
;             PG8_BAR; PG8_WAIT_L(0); PG8_MMA(0, 1, At, B1); PG8_BAR;
;             PG8_LDA(At, 0, 1); PG8_STAGE(PG8_SA(0, 0), a2, voffA);
;             PG8_BAR; PG8_WAIT_L(0); PG8_MMA(1, 0, At, B0); PG8_BAR; PG8_SCHED;
;             PG8_STAGE(PG8_SB(0, 1), b2 + hstep, voffB);
;             PG8_WAIT_V(6); PG8_BAR; PG8_MMA(1, 1, At, B1); PG8_BAR;
;             PG8_LDB(B0, 1, 0); PG8_SCHED; PG8_LDA(At, 1, 0); PG8_STAGE(PG8_SA(0, 1), a2 + hstep, voffA);
;             PG8_WAIT_L(8); PG8_BAR; PG8_WAIT_L(0); PG8_MMA(0, 0, At, B0); PG8_BAR; PG8_SCHED;
;             PG8_LDB(B1, 1, 1); PG8_STAGE(PG8_SB(1, 0), b3, voffB);
	s_waitcnt lgkmcnt(0)
	v_mfma_f32_16x16x32_bf16 v[116:119], v[240:243], v[182:185], v[116:119]
	v_mfma_f32_16x16x32_bf16 v[112:115], v[186:189], v[182:185], v[112:115]
	v_mfma_f32_16x16x32_bf16 v[100:103], v[240:243], v[194:197], v[100:103]
	v_mfma_f32_16x16x32_bf16 v[96:99], v[186:189], v[194:197], v[96:99]
	v_mfma_f32_16x16x32_bf16 v[84:87], v[240:243], v[224:227], v[84:87]
	v_mfma_f32_16x16x32_bf16 v[80:83], v[186:189], v[224:227], v[80:83]
	v_mfma_f32_16x16x32_bf16 v[68:71], v[240:243], v[232:235], v[68:71]
	v_mfma_f32_16x16x32_bf16 v[64:67], v[186:189], v[232:235], v[64:67]
	v_mfma_f32_16x16x32_bf16 v[116:119], v[244:247], v[190:193], v[116:119]
	v_mfma_f32_16x16x32_bf16 v[112:115], v[214:217], v[190:193], v[112:115]
	v_mfma_f32_16x16x32_bf16 v[100:103], v[244:247], v[220:223], v[100:103]
	v_mfma_f32_16x16x32_bf16 v[96:99], v[214:217], v[220:223], v[96:99]
	v_mfma_f32_16x16x32_bf16 v[84:87], v[244:247], v[228:231], v[84:87]
	v_mfma_f32_16x16x32_bf16 v[80:83], v[214:217], v[228:231], v[80:83]
	v_mfma_f32_16x16x32_bf16 v[68:71], v[244:247], v[236:239], v[68:71]
	v_mfma_f32_16x16x32_bf16 v[64:67], v[214:217], v[236:239], v[64:67]
	s_mov_b32 m0, s24
	v_lshl_add_u64 v[178:179], s[18:19], 0, v[142:143]
	s_barrier
	ds_read_b128 v[182:185], v219 offset:16384
	ds_read_b128 v[190:193], v219 offset:17408
	ds_read_b128 v[194:197], v219 offset:18432
	ds_read_b128 v[220:223], v219 offset:19456
	ds_read_b128 v[224:227], v219 offset:20480
	ds_read_b128 v[228:231], v219 offset:21504
	ds_read_b128 v[232:235], v219 offset:22528
	ds_read_b128 v[236:239], v219 offset:23552
	global_load_lds_dwordx4 v142, s[18:19]
	v_lshl_add_u64 v[248:249], s[18:19], 0, v[138:139]
	s_mov_b32 m0, s25
	s_nop 0
	global_load_lds_dwordx4 v138, s[18:19]
	s_barrier
	s_waitcnt lgkmcnt(0)
	v_mfma_f32_16x16x32_bf16 v[60:63], v[128:131], v[182:185], v[60:63]
	v_mfma_f32_16x16x32_bf16 v[56:59], v[150:153], v[182:185], v[56:59]
	v_mfma_f32_16x16x32_bf16 v[44:47], v[128:131], v[194:197], v[44:47]
	v_mfma_f32_16x16x32_bf16 v[40:43], v[150:153], v[194:197], v[40:43]
	v_mfma_f32_16x16x32_bf16 v[28:31], v[128:131], v[224:227], v[28:31]
	v_mfma_f32_16x16x32_bf16 v[24:27], v[150:153], v[224:227], v[24:27]
	v_mfma_f32_16x16x32_bf16 v[12:15], v[128:131], v[232:235], v[12:15]
	v_mfma_f32_16x16x32_bf16 v[8:11], v[150:153], v[232:235], v[8:11]
	v_mfma_f32_16x16x32_bf16 v[60:63], v[132:135], v[190:193], v[60:63]
	v_mfma_f32_16x16x32_bf16 v[56:59], v[174:177], v[190:193], v[56:59]
	v_mfma_f32_16x16x32_bf16 v[44:47], v[132:135], v[220:223], v[44:47]
	v_mfma_f32_16x16x32_bf16 v[40:43], v[174:177], v[220:223], v[40:43]
	v_mfma_f32_16x16x32_bf16 v[28:31], v[132:135], v[228:231], v[28:31]
	v_mfma_f32_16x16x32_bf16 v[24:27], v[174:177], v[228:231], v[24:27]
	v_mfma_f32_16x16x32_bf16 v[12:15], v[132:135], v[236:239], v[12:15]
	v_mfma_f32_16x16x32_bf16 v[8:11], v[174:177], v[236:239], v[8:11]
	s_barrier
	s_add_u32 s42, s16, 0x80000
	s_addc_u32 s43, s17, 0
	s_add_i32 s41, s44, s22
	s_mov_b32 m0, s41
	s_nop 0
	global_load_lds_dwordx4 v140, s[42:43]
	s_add_i32 m0, s41, 0x2000
	s_nop 0
	global_load_lds_dwordx4 v136, s[42:43]
	s_waitcnt vmcnt(6)
	s_barrier
	v_mfma_f32_16x16x32_bf16 v[52:55], v[240:243], v[182:185], v[52:55]
	v_mfma_f32_16x16x32_bf16 v[48:51], v[186:189], v[182:185], v[48:51]
	v_mfma_f32_16x16x32_bf16 v[36:39], v[240:243], v[194:197], v[36:39]
	v_mfma_f32_16x16x32_bf16 v[32:35], v[186:189], v[194:197], v[32:35]
	v_mfma_f32_16x16x32_bf16 v[20:23], v[240:243], v[224:227], v[20:23]
	v_mfma_f32_16x16x32_bf16 v[16:19], v[186:189], v[224:227], v[16:19]
	v_mfma_f32_16x16x32_bf16 v[4:7], v[240:243], v[232:235], v[4:7]
	v_mfma_f32_16x16x32_bf16 v[0:3], v[186:189], v[232:235], v[0:3]
	v_mfma_f32_16x16x32_bf16 v[52:55], v[244:247], v[190:193], v[52:55]
	v_mfma_f32_16x16x32_bf16 v[48:51], v[214:217], v[190:193], v[48:51]
	v_mfma_f32_16x16x32_bf16 v[36:39], v[244:247], v[220:223], v[36:39]
	v_mfma_f32_16x16x32_bf16 v[32:35], v[214:217], v[220:223], v[32:35]
	v_mfma_f32_16x16x32_bf16 v[20:23], v[244:247], v[228:231], v[20:23]
	v_mfma_f32_16x16x32_bf16 v[16:19], v[214:217], v[228:231], v[16:19]
	v_mfma_f32_16x16x32_bf16 v[4:7], v[244:247], v[236:239], v[4:7]
	v_mfma_f32_16x16x32_bf16 v[0:3], v[214:217], v[236:239], v[0:3]
	s_add_i32 s41, 0, 0x18000
	s_barrier
	ds_read_b128 v[128:131], v156 offset:32768
	ds_read_b128 v[132:135], v156 offset:33792
	ds_read_b128 v[150:153], v156 offset:34816
	ds_read_b128 v[174:177], v156 offset:35840
	s_add_u32 s18, s18, 0x80000
	s_addc_u32 s19, s19, 0
	s_mov_b32 m0, s26
	ds_read_b128 v[182:185], v219 offset:32768
	ds_read_b128 v[186:189], v219 offset:33792
	ds_read_b128 v[190:193], v219 offset:34816
	ds_read_b128 v[194:197], v219 offset:35840
	ds_read_b128 v[214:217], v219 offset:36864
	ds_read_b128 v[220:223], v219 offset:37888
	ds_read_b128 v[224:227], v219 offset:38912
	ds_read_b128 v[228:231], v219 offset:39936
	global_load_lds_dwordx4 v142, s[18:19]
	s_mov_b32 m0, s27
	s_nop 0
	global_load_lds_dwordx4 v138, s[18:19]
	s_waitcnt lgkmcnt(8)
	s_barrier
	s_waitcnt lgkmcnt(0)
	v_mfma_f32_16x16x32_bf16 v[124:127], v[128:131], v[182:185], v[124:127]
	v_mfma_f32_16x16x32_bf16 v[120:123], v[150:153], v[182:185], v[120:123]
	v_mfma_f32_16x16x32_bf16 v[108:111], v[128:131], v[190:193], v[108:111]
	v_mfma_f32_16x16x32_bf16 v[104:107], v[150:153], v[190:193], v[104:107]
	v_mfma_f32_16x16x32_bf16 v[92:95], v[128:131], v[214:217], v[92:95]
	v_mfma_f32_16x16x32_bf16 v[88:91], v[150:153], v[214:217], v[88:91]
	v_mfma_f32_16x16x32_bf16 v[76:79], v[128:131], v[224:227], v[76:79]
	v_mfma_f32_16x16x32_bf16 v[72:75], v[150:153], v[224:227], v[72:75]
	v_mfma_f32_16x16x32_bf16 v[124:127], v[132:135], v[186:189], v[124:127]
	v_mfma_f32_16x16x32_bf16 v[120:123], v[174:177], v[186:189], v[120:123]
	v_mfma_f32_16x16x32_bf16 v[108:111], v[132:135], v[194:197], v[108:111]
	v_mfma_f32_16x16x32_bf16 v[104:107], v[174:177], v[194:197], v[104:107]
	v_mfma_f32_16x16x32_bf16 v[92:95], v[132:135], v[220:223], v[92:95]
	v_mfma_f32_16x16x32_bf16 v[88:91], v[174:177], v[220:223], v[88:91]
	v_mfma_f32_16x16x32_bf16 v[76:79], v[132:135], v[228:231], v[76:79]
	v_mfma_f32_16x16x32_bf16 v[72:75], v[174:177], v[228:231], v[72:75]
	s_barrier
; #define PG8_STAGE(bufoff, gbase, voff) do { _Pragma("unroll") for (int _i = 0; _i < 2; ++_i) \
;         __builtin_amdgcn_global_load_lds((const unsigned*)((const char*)(gbase) + (voff)[_i]), (LAS unsigned*)(lds + (bufoff) + ldsw + _i * 8192), 16, 0, 0); } while (0)
; #define PG8_LDA(dst, b, h) do { _Pragma("unroll") for (int m = 0; m < 4; ++m) _Pragma("unroll") for (int k = 0; k < 2; ++k) dst[m][k] = *(const LAS bf16x8*)(lds + PG8_SA(b, h) + aoff + m * 2048 + k * 1024); } while (0)
; #define PG8_LDB(dst, b, h) do { _Pragma("unroll") for (int n = 0; n < 2; ++n) _Pragma("unroll") for (int k = 0; k < 2; ++k) dst[n][k] = *(const LAS bf16x8*)(lds + PG8_SB(b, h) + boff + n * 2048 + k * 1024); } while (0)
; #define PG8_MMA(ai, bj, At, Bt) do { __builtin_amdgcn_s_setprio(1); _Pragma("unroll") for (int m = 0; m < 4; ++m) _Pragma("unroll") for (int n = 0; n < 2; ++n) _Pragma("unroll") for (int k = 0; k < 2; ++k) \
;         acc[ai][bj][m][n] = __builtin_amdgcn_mfma_f32_16x16x32_bf16(Bt[n][k], At[m][k], acc[ai][bj][m][n], 0, 0, 0); __builtin_amdgcn_s_setprio(0); } while (0)
; #define PG8_WAIT_V(n) asm volatile("s_waitcnt vmcnt(" #n ")" ::: "memory")
; #define PG8_BAR __builtin_amdgcn_s_barrier()
; template <class Epi>
; DEV void gemm_phase(LAS unsigned char* lds, const Gemm g, const StaticOrder& S, const Epi& E) {
;     ...
;             PG8_WAIT_L(8); PG8_BAR; PG8_WAIT_L(0); PG8_MMA(0, 0, At, B0); PG8_BAR; PG8_SCHED;
;             PG8_LDB(B1, 1, 1); PG8_STAGE(PG8_SB(1, 0), b3, voffB);
;             PG8_BAR; PG8_WAIT_L(0); PG8_MMA(0, 1, At, B1); PG8_BAR;
;             PG8_LDA(At, 1, 1); PG8_STAGE(PG8_SA(1, 0), a3, voffA);
;             PG8_BAR; PG8_WAIT_L(0); PG8_MMA(1, 0, At, B0); PG8_BAR; PG8_SCHED;
;             PG8_STAGE(PG8_SB(1, 1), b3 + hstep, voffB);
;             PG8_WAIT_V(6); PG8_BAR; PG8_MMA(1, 1, At, B1); PG8_BAR;
;         }
;         E(acc, cur, wr, wc, fr, fq);
;     DEV void operator()(AccRef acc, const pg8::Unit& u, int wr, int wc, int fr, int fq) const {
;         const int ct = u.pn * 256, row0 = u.pm * 256 + wr * 64 + fr, cw = wc * 32 + 8 * fq;
;         if (ct < 4096) store_bf16_tile<1, true>(acc, UV, 4096, row0, ct + cw, ss);
;         else if (ct < 6144) store_bf16_tile<0, true>(acc, Z, 2048, row0, ct - 4096 + cw, ss);
;         else if (ct < 9216) store_bf16_tile<0, true>(acc, XBC, 3072, row0, ct - 6144 + cw, ss);
;         else if (wc == 0) {
	s_add_i32 s18, 0, 0x1c000
	s_add_i32 s19, s41, s22
	v_lshl_add_u64 v[154:155], v[154:155], 0, s[2:3]
	s_mov_b32 m0, s19
	ds_read_b128 v[232:235], v156 offset:49152
	ds_read_b128 v[236:239], v156 offset:50176
	ds_read_b128 v[240:243], v156 offset:51200
	ds_read_b128 v[244:247], v156 offset:52224
	global_load_lds_dwordx4 v[154:155], off
	v_lshl_add_u64 v[154:155], v[158:159], 0, s[2:3]
	s_add_i32 m0, s19, 0x2000
	s_nop 0
	global_load_lds_dwordx4 v[154:155], off
	s_barrier
	s_waitcnt lgkmcnt(0)
	v_mfma_f32_16x16x32_bf16 v[116:119], v[232:235], v[182:185], v[116:119]
	v_mfma_f32_16x16x32_bf16 v[112:115], v[240:243], v[182:185], v[112:115]
	v_mfma_f32_16x16x32_bf16 v[100:103], v[232:235], v[190:193], v[100:103]
	v_mfma_f32_16x16x32_bf16 v[96:99], v[240:243], v[190:193], v[96:99]
	v_mfma_f32_16x16x32_bf16 v[84:87], v[232:235], v[214:217], v[84:87]
	v_mfma_f32_16x16x32_bf16 v[80:83], v[240:243], v[214:217], v[80:83]
	v_mfma_f32_16x16x32_bf16 v[68:71], v[232:235], v[224:227], v[68:71]
	v_mfma_f32_16x16x32_bf16 v[64:67], v[240:243], v[224:227], v[64:67]
	v_mfma_f32_16x16x32_bf16 v[116:119], v[236:239], v[186:189], v[116:119]
	v_mfma_f32_16x16x32_bf16 v[112:115], v[244:247], v[186:189], v[112:115]
	v_mfma_f32_16x16x32_bf16 v[100:103], v[236:239], v[194:197], v[100:103]
	v_mfma_f32_16x16x32_bf16 v[96:99], v[244:247], v[194:197], v[96:99]
	v_mfma_f32_16x16x32_bf16 v[84:87], v[236:239], v[220:223], v[84:87]
	v_mfma_f32_16x16x32_bf16 v[80:83], v[244:247], v[220:223], v[80:83]
	v_mfma_f32_16x16x32_bf16 v[68:71], v[236:239], v[228:231], v[68:71]
	v_mfma_f32_16x16x32_bf16 v[64:67], v[244:247], v[228:231], v[64:67]
	s_mov_b32 m0, s28
	v_lshl_add_u64 v[154:155], v[178:179], 0, s[2:3]
	s_barrier
	ds_read_b128 v[182:185], v219 offset:49152
	ds_read_b128 v[186:189], v219 offset:50176
	ds_read_b128 v[190:193], v219 offset:51200
	ds_read_b128 v[194:197], v219 offset:52224
	ds_read_b128 v[214:217], v219 offset:53248
	ds_read_b128 v[220:223], v219 offset:54272
	ds_read_b128 v[224:227], v219 offset:55296
	ds_read_b128 v[228:231], v219 offset:56320
	global_load_lds_dwordx4 v[154:155], off
	v_lshl_add_u64 v[154:155], v[248:249], 0, s[2:3]
	s_mov_b32 m0, s29
	s_nop 0
	global_load_lds_dwordx4 v[154:155], off
	s_barrier
	s_waitcnt lgkmcnt(0)
	v_mfma_f32_16x16x32_bf16 v[60:63], v[128:131], v[182:185], v[60:63]
	v_mfma_f32_16x16x32_bf16 v[56:59], v[150:153], v[182:185], v[56:59]
	v_mfma_f32_16x16x32_bf16 v[44:47], v[128:131], v[190:193], v[44:47]
	v_mfma_f32_16x16x32_bf16 v[40:43], v[150:153], v[190:193], v[40:43]
	v_mfma_f32_16x16x32_bf16 v[28:31], v[128:131], v[214:217], v[28:31]
	v_mfma_f32_16x16x32_bf16 v[24:27], v[150:153], v[214:217], v[24:27]
	v_mfma_f32_16x16x32_bf16 v[12:15], v[128:131], v[224:227], v[12:15]
	v_mfma_f32_16x16x32_bf16 v[8:11], v[150:153], v[224:227], v[8:11]
	v_mfma_f32_16x16x32_bf16 v[60:63], v[132:135], v[186:189], v[60:63]
	v_mfma_f32_16x16x32_bf16 v[56:59], v[174:177], v[186:189], v[56:59]
	v_mfma_f32_16x16x32_bf16 v[44:47], v[132:135], v[194:197], v[44:47]
	v_mfma_f32_16x16x32_bf16 v[40:43], v[174:177], v[194:197], v[40:43]
	v_mfma_f32_16x16x32_bf16 v[28:31], v[132:135], v[220:223], v[28:31]
	v_mfma_f32_16x16x32_bf16 v[24:27], v[174:177], v[220:223], v[24:27]
	v_mfma_f32_16x16x32_bf16 v[12:15], v[132:135], v[228:231], v[12:15]
	v_mfma_f32_16x16x32_bf16 v[8:11], v[174:177], v[228:231], v[8:11]
	s_barrier
	s_add_u32 s16, s16, 0x80080
	s_addc_u32 s17, s17, 0
	s_add_i32 s18, s18, s22
	s_mov_b32 m0, s18
	s_nop 0
	global_load_lds_dwordx4 v140, s[16:17]
	s_add_i32 m0, s18, 0x2000
	s_nop 0
	global_load_lds_dwordx4 v136, s[16:17]
	s_waitcnt vmcnt(6)
	s_barrier
	v_mfma_f32_16x16x32_bf16 v[52:55], v[232:235], v[182:185], v[52:55]
	v_mfma_f32_16x16x32_bf16 v[48:51], v[240:243], v[182:185], v[48:51]
	v_mfma_f32_16x16x32_bf16 v[36:39], v[232:235], v[190:193], v[36:39]
	v_mfma_f32_16x16x32_bf16 v[32:35], v[240:243], v[190:193], v[32:35]
	v_mfma_f32_16x16x32_bf16 v[20:23], v[232:235], v[214:217], v[20:23]
	v_mfma_f32_16x16x32_bf16 v[16:19], v[240:243], v[214:217], v[16:19]
	v_mfma_f32_16x16x32_bf16 v[4:7], v[232:235], v[224:227], v[4:7]
	v_mfma_f32_16x16x32_bf16 v[0:3], v[240:243], v[224:227], v[0:3]
	v_mfma_f32_16x16x32_bf16 v[52:55], v[236:239], v[186:189], v[52:55]
	v_mfma_f32_16x16x32_bf16 v[48:51], v[244:247], v[186:189], v[48:51]
	v_mfma_f32_16x16x32_bf16 v[36:39], v[236:239], v[194:197], v[36:39]
	v_mfma_f32_16x16x32_bf16 v[32:35], v[244:247], v[194:197], v[32:35]
	v_mfma_f32_16x16x32_bf16 v[20:23], v[236:239], v[220:223], v[20:23]
	v_mfma_f32_16x16x32_bf16 v[16:19], v[244:247], v[220:223], v[16:19]
	v_mfma_f32_16x16x32_bf16 v[4:7], v[236:239], v[228:231], v[4:7]
	v_mfma_f32_16x16x32_bf16 v[0:3], v[244:247], v[228:231], v[0:3]
	s_add_i32 s40, s40, 2
	s_add_u32 s14, s14, 0x100
	s_addc_u32 s15, s15, 0
	s_add_u32 s36, s36, 0x100
	s_addc_u32 s37, s37, 0
	s_cmp_gt_u32 s40, 29
	s_barrier
	s_cbranch_scc0 .LBB0_588
	s_lshl_b32 s7, s34, 8
	v_lshl_add_u32 v150, s0, 8, v157
	s_cmp_gt_i32 s34, 15
	s_mov_b64 s[0:1], -1
	s_cbranch_scc0 .LBB0_601
	s_cmp_gt_u32 s34, 23
	s_cbranch_scc0 .LBB0_598
	s_cmp_gt_u32 s34, 35
	s_cbranch_scc0 .LBB0_595
	s_andn2_b64 vcc, exec, s[4:5]
	s_cbranch_vccnz .LBB0_594
; DEV float rowscale(const float* ss, int row) { const f32x4 a = *(const f32x4*)(ss + (size_t)row * 8), b = *(const f32x4*)(ss + (size_t)row * 8 + 4);
;     return rsqrtf(((a[0] + a[1]) + (a[2] + a[3]) + (b[0] + b[1]) + (b[2] + b[3])) * (1.0f / 2048.0f) + EPS); }
;     DEV void operator()(AccRef acc, const pg8::Unit& u, int wr, int wc, int fr, int fq) const {
;     ...
;         else if (wc == 0) {
; #pragma unroll
;             for (int ai = 0; ai < 2; ++ai)
; #pragma unroll
;                 for (int m = 0; m < 4; ++m) { const float rs = rowscale(ss, row0 + ai * 128 + m * 16);
; #pragma unroll
;                     for (int n = 0; n < 2; ++n) *(f32x4*)(DTR + (size_t)(row0 + ai * 128 + m * 16) * 32 + 8 * fq + 4 * n) = acc[ai][0][m][n] * rs; }
	v_ashrrev_i32_e32 v151, 31, v150
	v_readlane_b32 s0, v251, 39
	v_lshlrev_b64 v[128:129], 5, v[150:151]
	v_readlane_b32 s1, v251, 40
	s_mov_b32 s9, 0x800000
	s_nop 0
	v_lshl_add_u64 v[132:133], s[0:1], 0, v[128:129]
	global_load_dwordx4 v[128:131], v[132:133], off offset:16
	s_nop 0
	global_load_dwordx4 v[132:135], v[132:133], off
	s_waitcnt vmcnt(0)
	v_mov_b32_e32 v152, v133
	v_mov_b32_e32 v153, v134
	v_mov_b32_e32 v133, v135
	v_pk_add_f32 v[132:133], v[152:153], v[132:133]
	v_mov_b32_e32 v134, v130
	v_mov_b32_e32 v135, v128
	v_mov_b32_e32 v128, v131
	v_pk_add_f32 v[128:129], v[134:135], v[128:129]
	v_add_f32_e32 v130, v132, v133
	v_add_f32_e32 v129, v130, v129
	v_add_f32_e32 v128, v128, v129
	v_fmamk_f32 v128, v128, 0x3a000000, v199
	v_cmp_gt_f32_e32 vcc, s9, v128
	v_mul_f32_e32 v129, 0x4b800000, v128
	v_lshlrev_b64 v[134:135], 7, v[150:151]
	v_cndmask_b32_e32 v128, v128, v129, vcc
	v_rsq_f32_e32 v128, v128
	v_lshl_add_u64 v[134:135], v[144:145], 0, v[134:135]
	v_or_b32_e32 v152, 16, v150
	v_ashrrev_i32_e32 v153, 31, v152
	v_mul_f32_e32 v129, 0x45800000, v128
	v_cndmask_b32_e32 v132, v128, v129, vcc
	v_pk_mul_f32 v[130:131], v[126:127], v[132:133] op_sel_hi:[1,0]
	v_pk_mul_f32 v[128:129], v[124:125], v[132:133] op_sel_hi:[1,0]
	global_store_dwordx4 v[134:135], v[128:131], off
	s_nop 1
	v_pk_mul_f32 v[130:131], v[122:123], v[132:133] op_sel_hi:[1,0]
	v_pk_mul_f32 v[128:129], v[120:121], v[132:133] op_sel_hi:[1,0]
	global_store_dwordx4 v[134:135], v[128:131], off offset:16
	s_nop 1
	v_lshlrev_b64 v[128:129], 5, v[152:153]
	v_lshl_add_u64 v[132:133], s[0:1], 0, v[128:129]
	global_load_dwordx4 v[128:131], v[132:133], off offset:16
	s_nop 0
	global_load_dwordx4 v[132:135], v[132:133], off
	s_waitcnt vmcnt(0)
	v_mov_b32_e32 v154, v133
	v_mov_b32_e32 v155, v134
	v_mov_b32_e32 v133, v135
	v_pk_add_f32 v[132:133], v[154:155], v[132:133]
	v_mov_b32_e32 v134, v130
	v_mov_b32_e32 v135, v128
	v_mov_b32_e32 v128, v131
	v_pk_add_f32 v[128:129], v[134:135], v[128:129]
	v_add_f32_e32 v130, v132, v133
	v_add_f32_e32 v129, v130, v129
	v_add_f32_e32 v128, v128, v129
	v_fmamk_f32 v128, v128, 0x3a000000, v199
	v_cmp_gt_f32_e32 vcc, s9, v128
	v_mul_f32_e32 v129, 0x4b800000, v128
	v_lshlrev_b64 v[134:135], 7, v[152:153]
	v_cndmask_b32_e32 v128, v128, v129, vcc
	v_rsq_f32_e32 v128, v128
	v_lshl_add_u64 v[134:135], v[144:145], 0, v[134:135]
	v_or_b32_e32 v152, 32, v150
	v_ashrrev_i32_e32 v153, 31, v152
	v_mul_f32_e32 v129, 0x45800000, v128
	v_cndmask_b32_e32 v132, v128, v129, vcc
	v_pk_mul_f32 v[130:131], v[110:111], v[132:133] op_sel_hi:[1,0]
	v_pk_mul_f32 v[128:129], v[108:109], v[132:133] op_sel_hi:[1,0]
	global_store_dwordx4 v[134:135], v[128:131], off
	s_nop 1
	v_pk_mul_f32 v[130:131], v[106:107], v[132:133] op_sel_hi:[1,0]
	v_pk_mul_f32 v[128:129], v[104:105], v[132:133] op_sel_hi:[1,0]
	global_store_dwordx4 v[134:135], v[128:131], off offset:16
	s_nop 1
	v_lshlrev_b64 v[128:129], 5, v[152:153]
	v_lshl_add_u64 v[132:133], s[0:1], 0, v[128:129]
	global_load_dwordx4 v[128:131], v[132:133], off offset:16
	s_nop 0
	global_load_dwordx4 v[132:135], v[132:133], off
	s_waitcnt vmcnt(0)
	v_mov_b32_e32 v154, v133
	v_mov_b32_e32 v155, v134
	v_mov_b32_e32 v133, v135
	v_pk_add_f32 v[132:133], v[154:155], v[132:133]
	v_mov_b32_e32 v134, v130
	v_mov_b32_e32 v135, v128
	v_mov_b32_e32 v128, v131
	v_pk_add_f32 v[128:129], v[134:135], v[128:129]
	v_add_f32_e32 v130, v132, v133
	v_add_f32_e32 v129, v130, v129
	v_add_f32_e32 v128, v128, v129
	v_fmamk_f32 v128, v128, 0x3a000000, v199
	v_cmp_gt_f32_e32 vcc, s9, v128
	v_mul_f32_e32 v129, 0x4b800000, v128
	v_lshlrev_b64 v[134:135], 7, v[152:153]
	v_cndmask_b32_e32 v128, v128, v129, vcc
	v_rsq_f32_e32 v128, v128
	v_lshl_add_u64 v[134:135], v[144:145], 0, v[134:135]
	v_or_b32_e32 v152, 48, v150
	v_ashrrev_i32_e32 v153, 31, v152
	v_mul_f32_e32 v129, 0x45800000, v128
	v_cndmask_b32_e32 v132, v128, v129, vcc
	v_pk_mul_f32 v[130:131], v[94:95], v[132:133] op_sel_hi:[1,0]
	v_pk_mul_f32 v[128:129], v[92:93], v[132:133] op_sel_hi:[1,0]
	global_store_dwordx4 v[134:135], v[128:131], off
	s_nop 1
	v_pk_mul_f32 v[130:131], v[90:91], v[132:133] op_sel_hi:[1,0]
	v_pk_mul_f32 v[128:129], v[88:89], v[132:133] op_sel_hi:[1,0]
	global_store_dwordx4 v[134:135], v[128:131], off offset:16
	s_nop 1
	v_lshlrev_b64 v[128:129], 5, v[152:153]
	v_lshl_add_u64 v[132:133], s[0:1], 0, v[128:129]
	global_load_dwordx4 v[128:131], v[132:133], off offset:16
	s_nop 0
	global_load_dwordx4 v[132:135], v[132:133], off
	s_waitcnt vmcnt(0)
	v_mov_b32_e32 v154, v133
	v_mov_b32_e32 v155, v134
	v_mov_b32_e32 v133, v135
	v_pk_add_f32 v[132:133], v[154:155], v[132:133]
	v_mov_b32_e32 v134, v130
	v_mov_b32_e32 v135, v128
	v_mov_b32_e32 v128, v131
	v_pk_add_f32 v[128:129], v[134:135], v[128:129]
	v_add_f32_e32 v130, v132, v133
	v_add_f32_e32 v129, v130, v129
	v_add_f32_e32 v128, v128, v129
	v_fmamk_f32 v128, v128, 0x3a000000, v199
	v_cmp_gt_f32_e32 vcc, s9, v128
	v_mul_f32_e32 v129, 0x4b800000, v128
	v_lshlrev_b64 v[134:135], 7, v[152:153]
	v_cndmask_b32_e32 v128, v128, v129, vcc
	v_rsq_f32_e32 v128, v128
	v_lshl_add_u64 v[134:135], v[144:145], 0, v[134:135]
	v_add_u32_e32 v152, 0x80, v150
	v_ashrrev_i32_e32 v153, 31, v152
	v_mul_f32_e32 v129, 0x45800000, v128
	v_cndmask_b32_e32 v132, v128, v129, vcc
	v_pk_mul_f32 v[130:131], v[78:79], v[132:133] op_sel_hi:[1,0]
	v_pk_mul_f32 v[128:129], v[76:77], v[132:133] op_sel_hi:[1,0]
	global_store_dwordx4 v[134:135], v[128:131], off
	s_nop 1
	v_pk_mul_f32 v[130:131], v[74:75], v[132:133] op_sel_hi:[1,0]
	v_pk_mul_f32 v[128:129], v[72:73], v[132:133] op_sel_hi:[1,0]
	global_store_dwordx4 v[134:135], v[128:131], off offset:16
	s_nop 1
	v_lshlrev_b64 v[128:129], 5, v[152:153]
	v_lshl_add_u64 v[132:133], s[0:1], 0, v[128:129]
	global_load_dwordx4 v[128:131], v[132:133], off offset:16
	s_nop 0
	global_load_dwordx4 v[132:135], v[132:133], off
	s_waitcnt vmcnt(0)
; DEV float rowscale(const float* ss, int row) { const f32x4 a = *(const f32x4*)(ss + (size_t)row * 8), b = *(const f32x4*)(ss + (size_t)row * 8 + 4);
;     return rsqrtf(((a[0] + a[1]) + (a[2] + a[3]) + (b[0] + b[1]) + (b[2] + b[3])) * (1.0f / 2048.0f) + EPS); }
;     DEV void operator()(AccRef acc, const pg8::Unit& u, int wr, int wc, int fr, int fq) const {
;     ...
;         else if (wc == 0) {
; #pragma unroll
;             for (int ai = 0; ai < 2; ++ai)
; #pragma unroll
;                 for (int m = 0; m < 4; ++m) { const float rs = rowscale(ss, row0 + ai * 128 + m * 16);
; #pragma unroll
;                     for (int n = 0; n < 2; ++n) *(f32x4*)(DTR + (size_t)(row0 + ai * 128 + m * 16) * 32 + 8 * fq + 4 * n) = acc[ai][0][m][n] * rs; }
	v_mov_b32_e32 v154, v133
	v_mov_b32_e32 v155, v134
	v_mov_b32_e32 v133, v135
	v_pk_add_f32 v[132:133], v[154:155], v[132:133]
	v_mov_b32_e32 v134, v130
	v_mov_b32_e32 v135, v128
	v_mov_b32_e32 v128, v131
	v_pk_add_f32 v[128:129], v[134:135], v[128:129]
	v_add_f32_e32 v130, v132, v133
	v_add_f32_e32 v129, v130, v129
	v_add_f32_e32 v128, v128, v129
	v_fmamk_f32 v128, v128, 0x3a000000, v199
	v_cmp_gt_f32_e32 vcc, s9, v128
	v_mul_f32_e32 v129, 0x4b800000, v128
	v_lshlrev_b64 v[134:135], 7, v[152:153]
	v_cndmask_b32_e32 v128, v128, v129, vcc
	v_rsq_f32_e32 v128, v128
	v_lshl_add_u64 v[134:135], v[144:145], 0, v[134:135]
	v_add_u32_e32 v152, 0x90, v150
	v_ashrrev_i32_e32 v153, 31, v152
	v_mul_f32_e32 v129, 0x45800000, v128
	v_cndmask_b32_e32 v132, v128, v129, vcc
	v_pk_mul_f32 v[130:131], v[62:63], v[132:133] op_sel_hi:[1,0]
	v_pk_mul_f32 v[128:129], v[60:61], v[132:133] op_sel_hi:[1,0]
	global_store_dwordx4 v[134:135], v[128:131], off
	s_nop 1
	v_pk_mul_f32 v[130:131], v[58:59], v[132:133] op_sel_hi:[1,0]
	v_pk_mul_f32 v[128:129], v[56:57], v[132:133] op_sel_hi:[1,0]
	global_store_dwordx4 v[134:135], v[128:131], off offset:16
	s_nop 1
	v_lshlrev_b64 v[128:129], 5, v[152:153]
	v_lshl_add_u64 v[132:133], s[0:1], 0, v[128:129]
	global_load_dwordx4 v[128:131], v[132:133], off offset:16
	s_nop 0
	global_load_dwordx4 v[132:135], v[132:133], off
	s_waitcnt vmcnt(0)
	v_mov_b32_e32 v154, v133
	v_mov_b32_e32 v155, v134
	v_mov_b32_e32 v133, v135
	v_pk_add_f32 v[132:133], v[154:155], v[132:133]
	v_mov_b32_e32 v134, v130
	v_mov_b32_e32 v135, v128
	v_mov_b32_e32 v128, v131
	v_pk_add_f32 v[128:129], v[134:135], v[128:129]
	v_add_f32_e32 v130, v132, v133
	v_add_f32_e32 v129, v130, v129
	v_add_f32_e32 v128, v128, v129
	v_fmamk_f32 v128, v128, 0x3a000000, v199
	v_cmp_gt_f32_e32 vcc, s9, v128
	v_mul_f32_e32 v129, 0x4b800000, v128
	v_lshlrev_b64 v[134:135], 7, v[152:153]
	v_cndmask_b32_e32 v128, v128, v129, vcc
	v_rsq_f32_e32 v128, v128
	v_lshl_add_u64 v[134:135], v[144:145], 0, v[134:135]
	v_add_u32_e32 v152, 0xa0, v150
	v_ashrrev_i32_e32 v153, 31, v152
	v_mul_f32_e32 v129, 0x45800000, v128
	v_cndmask_b32_e32 v132, v128, v129, vcc
	v_pk_mul_f32 v[130:131], v[46:47], v[132:133] op_sel_hi:[1,0]
	v_pk_mul_f32 v[128:129], v[44:45], v[132:133] op_sel_hi:[1,0]
	global_store_dwordx4 v[134:135], v[128:131], off
	s_nop 1
	v_pk_mul_f32 v[130:131], v[42:43], v[132:133] op_sel_hi:[1,0]
	v_pk_mul_f32 v[128:129], v[40:41], v[132:133] op_sel_hi:[1,0]
	global_store_dwordx4 v[134:135], v[128:131], off offset:16
	s_nop 1
	v_lshlrev_b64 v[128:129], 5, v[152:153]
	v_lshl_add_u64 v[132:133], s[0:1], 0, v[128:129]
	global_load_dwordx4 v[128:131], v[132:133], off offset:16
	s_nop 0
	global_load_dwordx4 v[132:135], v[132:133], off
	s_waitcnt vmcnt(0)
	v_mov_b32_e32 v154, v133
	v_mov_b32_e32 v155, v134
	v_mov_b32_e32 v133, v135
	v_pk_add_f32 v[132:133], v[154:155], v[132:133]
	v_mov_b32_e32 v134, v130
	v_mov_b32_e32 v135, v128
	v_mov_b32_e32 v128, v131
	v_pk_add_f32 v[128:129], v[134:135], v[128:129]
	v_add_f32_e32 v130, v132, v133
	v_add_f32_e32 v129, v130, v129
	v_add_f32_e32 v128, v128, v129
	v_fmamk_f32 v128, v128, 0x3a000000, v199
	v_cmp_gt_f32_e32 vcc, s9, v128
	v_mul_f32_e32 v129, 0x4b800000, v128
	v_lshlrev_b64 v[134:135], 7, v[152:153]
	v_cndmask_b32_e32 v128, v128, v129, vcc
	v_rsq_f32_e32 v128, v128
	v_lshl_add_u64 v[134:135], v[144:145], 0, v[134:135]
	v_add_u32_e32 v152, 0xb0, v150
	v_ashrrev_i32_e32 v153, 31, v152
	v_mul_f32_e32 v129, 0x45800000, v128
	v_cndmask_b32_e32 v132, v128, v129, vcc
	v_pk_mul_f32 v[130:131], v[30:31], v[132:133] op_sel_hi:[1,0]
	v_pk_mul_f32 v[128:129], v[28:29], v[132:133] op_sel_hi:[1,0]
	global_store_dwordx4 v[134:135], v[128:131], off
	s_nop 1
	v_pk_mul_f32 v[130:131], v[26:27], v[132:133] op_sel_hi:[1,0]
	v_pk_mul_f32 v[128:129], v[24:25], v[132:133] op_sel_hi:[1,0]
	global_store_dwordx4 v[134:135], v[128:131], off offset:16
	s_nop 1
	v_lshlrev_b64 v[128:129], 5, v[152:153]
	v_lshl_add_u64 v[132:133], s[0:1], 0, v[128:129]
	global_load_dwordx4 v[128:131], v[132:133], off offset:16
	s_nop 0
	global_load_dwordx4 v[132:135], v[132:133], off
	s_waitcnt vmcnt(0)
	v_mov_b32_e32 v154, v133
	v_mov_b32_e32 v155, v134
	v_mov_b32_e32 v133, v135
	v_pk_add_f32 v[132:133], v[154:155], v[132:133]
	v_mov_b32_e32 v134, v130
	v_mov_b32_e32 v135, v128
	v_mov_b32_e32 v128, v131
	v_pk_add_f32 v[128:129], v[134:135], v[128:129]
	v_add_f32_e32 v130, v132, v133
	v_add_f32_e32 v129, v130, v129
	v_add_f32_e32 v128, v128, v129
	v_fmamk_f32 v128, v128, 0x3a000000, v199
	v_cmp_gt_f32_e32 vcc, s9, v128
	v_mul_f32_e32 v129, 0x4b800000, v128
	v_lshlrev_b64 v[134:135], 7, v[152:153]
	v_cndmask_b32_e32 v128, v128, v129, vcc
	v_rsq_f32_e32 v128, v128
	v_lshl_add_u64 v[134:135], v[144:145], 0, v[134:135]
	v_mul_f32_e32 v129, 0x45800000, v128
	v_cndmask_b32_e32 v132, v128, v129, vcc
	v_pk_mul_f32 v[130:131], v[14:15], v[132:133] op_sel_hi:[1,0]
	v_pk_mul_f32 v[128:129], v[12:13], v[132:133] op_sel_hi:[1,0]
	global_store_dwordx4 v[134:135], v[128:131], off
	s_nop 1
	v_pk_mul_f32 v[130:131], v[10:11], v[132:133] op_sel_hi:[1,0]
	v_pk_mul_f32 v[128:129], v[8:9], v[132:133] op_sel_hi:[1,0]
	global_store_dwordx4 v[134:135], v[128:131], off offset:16

; #define PG8_STAGE(bufoff, gbase, voff) do { _Pragma("unroll") for (int _i = 0; _i < 2; ++_i) \
;         __builtin_amdgcn_global_load_lds((const unsigned*)((const char*)(gbase) + (voff)[_i]), (LAS unsigned*)(lds + (bufoff) + ldsw + _i * 8192), 16, 0, 0); } while (0)
; #define PG8_LDA(dst, b, h) do { _Pragma("unroll") for (int m = 0; m < 4; ++m) _Pragma("unroll") for (int k = 0; k < 2; ++k) dst[m][k] = *(const LAS bf16x8*)(lds + PG8_SA(b, h) + aoff + m * 2048 + k * 1024); } while (0)
; #define PG8_LDB(dst, b, h) do { _Pragma("unroll") for (int n = 0; n < 2; ++n) _Pragma("unroll") for (int k = 0; k < 2; ++k) dst[n][k] = *(const LAS bf16x8*)(lds + PG8_SB(b, h) + boff + n * 2048 + k * 1024); } while (0)
; #define PG8_WAIT_L(n) asm volatile("s_waitcnt lgkmcnt(" #n ")" ::: "memory")
; #define PG8_BAR __builtin_amdgcn_s_barrier()
; #define PG8_SCHED __builtin_amdgcn_sched_barrier(0)
; template <class Epi>
; DEV void gemm_phase(LAS unsigned char* lds, const Gemm g, const StaticOrder& S, const Epi& E) {
;     ...
;         const char* nA = has_next ? (const char*)g.A + (size_t)nxt.pm * tstep : cA; const char* nB = has_next ? (const char*)g.Bt + (size_t)nxt.pn * tstep : cB;
;         for (int t = 0; t < nt; t += 2) {
;             const bool last = (t == nt - 2);
;             const char* a1 = cA + (size_t)(t + 1) * kstep;
;             const char* a2 = last ? nA : cA + (size_t)(t + 2) * kstep; const char* b2 = last ? nB : cB + (size_t)(t + 2) * kstep;
;             const char* a3 = a2 + kstep; const char* b3 = b2 + kstep;
;             PG8_LDB(B0, 0, 0); PG8_SCHED; PG8_LDA(At, 0, 0); PG8_STAGE(PG8_SA(1, 1), a1 + hstep, voffA);
;             PG8_WAIT_L(8); PG8_BAR; PG8_WAIT_L(0); PG8_MMA(0, 0, At, B0); PG8_BAR; PG8_SCHED;
;             PG8_LDB(B1, 0, 1); PG8_STAGE(PG8_SB(0, 0), b2, voffB);
;             PG8_BAR; PG8_WAIT_L(0); PG8_MMA(0, 1, At, B1); PG8_BAR;
;     ...
; #pragma unroll
;         for (int a = 0; a < 2; ++a)
; #pragma unroll
;             for (int b = 0; b < 2; ++b)
; #pragma unroll
;                 for (int m = 0; m < 4; ++m)
; #pragma unroll
;                     for (int n = 0; n < 2; ++n) acc[a][b][m][n] = (f32x4){0.f, 0.f, 0.f, 0.f};
;         cur = nxt; cA = nA; cB = nB; ++ui;
.LBB0_754:
	s_ashr_i32 s15, s14, 31
	v_cmp_lt_i64_e32 vcc, s[16:17], v[168:169]
	s_lshl_b64 s[16:17], s[14:15], 20
	v_readlane_b32 s18, v250, 9
	v_readlane_b32 s19, v250, 10
	s_add_u32 s16, s18, s16
	s_addc_u32 s17, s19, s17
	s_and_b64 s[18:19], vcc, exec
	s_cselect_b32 s5, s17, s21
	s_cselect_b32 s15, s16, s20
	s_ashr_i32 s11, s10, 31
	s_lshl_b64 s[18:19], s[10:11], 20
	s_add_u32 s18, s28, s18
	s_addc_u32 s19, s29, s19
	s_and_b64 s[24:25], vcc, exec
	s_cselect_b32 s11, s19, s23
	s_cselect_b32 s43, s18, s22
	s_add_u32 s20, s20, 0x80080
	s_addc_u32 s21, s21, 0
	s_add_u32 s44, s22, 0x100
	s_addc_u32 s45, s23, 0
	s_mov_b32 s46, -2
	v_mov_b64_e32 v[0:1], 0
	v_mov_b64_e32 v[2:3], 0
	v_mov_b64_e32 v[4:5], 0
	v_mov_b64_e32 v[6:7], 0
	v_mov_b64_e32 v[8:9], 0
	v_mov_b64_e32 v[10:11], 0
	v_mov_b64_e32 v[12:13], 0
	v_mov_b64_e32 v[14:15], 0
	v_mov_b64_e32 v[16:17], 0
	v_mov_b64_e32 v[18:19], 0
	v_mov_b64_e32 v[20:21], 0
	v_mov_b64_e32 v[22:23], 0
	v_mov_b64_e32 v[24:25], 0
	v_mov_b64_e32 v[26:27], 0
	v_mov_b64_e32 v[28:29], 0
	v_mov_b64_e32 v[30:31], 0
	v_mov_b64_e32 v[32:33], 0
	v_mov_b64_e32 v[34:35], 0
	v_mov_b64_e32 v[36:37], 0
	v_mov_b64_e32 v[38:39], 0
	v_mov_b64_e32 v[40:41], 0
	v_mov_b64_e32 v[42:43], 0
	v_mov_b64_e32 v[44:45], 0
	v_mov_b64_e32 v[46:47], 0
	v_mov_b64_e32 v[48:49], 0
	v_mov_b64_e32 v[50:51], 0
	v_mov_b64_e32 v[52:53], 0
	v_mov_b64_e32 v[54:55], 0
	v_mov_b64_e32 v[56:57], 0
	v_mov_b64_e32 v[58:59], 0
	v_mov_b64_e32 v[60:61], 0
	v_mov_b64_e32 v[62:63], 0
	v_mov_b64_e32 v[64:65], 0
	v_mov_b64_e32 v[66:67], 0
	v_mov_b64_e32 v[68:69], 0
	v_mov_b64_e32 v[70:71], 0
	v_mov_b64_e32 v[72:73], 0
	v_mov_b64_e32 v[74:75], 0
	v_mov_b64_e32 v[76:77], 0
	v_mov_b64_e32 v[78:79], 0
	v_mov_b64_e32 v[80:81], 0
	v_mov_b64_e32 v[82:83], 0
	v_mov_b64_e32 v[84:85], 0
	v_mov_b64_e32 v[86:87], 0
	v_mov_b64_e32 v[88:89], 0
	v_mov_b64_e32 v[90:91], 0
	v_mov_b64_e32 v[92:93], 0
	v_mov_b64_e32 v[94:95], 0
	v_mov_b64_e32 v[96:97], 0
	v_mov_b64_e32 v[98:99], 0
	v_mov_b64_e32 v[100:101], 0
	v_mov_b64_e32 v[102:103], 0
	v_mov_b64_e32 v[104:105], 0
	v_mov_b64_e32 v[106:107], 0
	v_mov_b64_e32 v[108:109], 0
	v_mov_b64_e32 v[110:111], 0
	v_mov_b64_e32 v[112:113], 0
	v_mov_b64_e32 v[114:115], 0
	v_mov_b64_e32 v[116:117], 0
	v_mov_b64_e32 v[118:119], 0
	v_mov_b64_e32 v[120:121], 0
	v_mov_b64_e32 v[122:123], 0
	v_mov_b64_e32 v[124:125], 0
	v_mov_b64_e32 v[126:127], 0
	v_add_u32_e32 v148, 0x10000, v155
.LBB0_755:
	s_add_u32 s22, s20, 0xfff80080
	s_addc_u32 s23, s21, -1
	s_add_i32 s47, 0, 0x10000
	ds_read_b128 v[128:131], v148
	ds_read_b128 v[132:135], v148 offset:1024
	ds_read_b128 v[150:153], v148 offset:2048
	ds_read_b128 v[174:177], v148 offset:3072
	s_cmp_eq_u32 s46, 28
	s_cselect_b32 s25, s5, s23
	s_cselect_b32 s24, s15, s22
	s_cselect_b32 s23, s11, s45
	s_cselect_b32 s22, s43, s44
	s_add_i32 m0, s34, 0xc000
	ds_read_b128 v[178:181], v167
	ds_read_b128 v[182:185], v167 offset:1024
	ds_read_b128 v[186:189], v167 offset:2048
	ds_read_b128 v[190:193], v167 offset:3072
	ds_read_b128 v[194:197], v167 offset:4096
	ds_read_b128 v[218:221], v167 offset:5120
	ds_read_b128 v[222:225], v167 offset:6144
	ds_read_b128 v[226:229], v167 offset:7168
	global_load_lds_dwordx4 v142, s[20:21]
	s_add_i32 m0, s34, 0xe000
	s_nop 0
	global_load_lds_dwordx4 v144, s[20:21]
	s_waitcnt lgkmcnt(8)
	s_barrier
	s_waitcnt lgkmcnt(0)
	v_mfma_f32_16x16x32_bf16 v[124:127], v[128:131], v[178:181], v[124:127]
	v_mfma_f32_16x16x32_bf16 v[116:119], v[150:153], v[178:181], v[116:119]
	v_mfma_f32_16x16x32_bf16 v[108:111], v[128:131], v[186:189], v[108:111]
	v_mfma_f32_16x16x32_bf16 v[100:103], v[150:153], v[186:189], v[100:103]
	v_mfma_f32_16x16x32_bf16 v[92:95], v[128:131], v[194:197], v[92:95]
	v_mfma_f32_16x16x32_bf16 v[84:87], v[150:153], v[194:197], v[84:87]
	v_mfma_f32_16x16x32_bf16 v[76:79], v[128:131], v[222:225], v[76:79]
	v_mfma_f32_16x16x32_bf16 v[68:71], v[150:153], v[222:225], v[68:71]
	v_mfma_f32_16x16x32_bf16 v[124:127], v[132:135], v[182:185], v[124:127]
	v_mfma_f32_16x16x32_bf16 v[116:119], v[174:177], v[182:185], v[116:119]
	v_mfma_f32_16x16x32_bf16 v[108:111], v[132:135], v[190:193], v[108:111]
	v_mfma_f32_16x16x32_bf16 v[100:103], v[174:177], v[190:193], v[100:103]
	v_mfma_f32_16x16x32_bf16 v[92:95], v[132:135], v[218:221], v[92:95]
	v_mfma_f32_16x16x32_bf16 v[84:87], v[174:177], v[218:221], v[84:87]
	v_mfma_f32_16x16x32_bf16 v[76:79], v[132:135], v[226:229], v[76:79]
	v_mfma_f32_16x16x32_bf16 v[68:71], v[174:177], v[226:229], v[68:71]
	s_barrier
	s_add_i32 s50, 0, 0x14000
	s_add_i32 s47, s47, s30
	ds_read_b128 v[230:233], v148 offset:16384
	ds_read_b128 v[234:237], v148 offset:17408
	ds_read_b128 v[238:241], v148 offset:18432
	ds_read_b128 v[242:245], v148 offset:19456
	v_lshl_add_u64 v[146:147], s[22:23], 0, v[160:161]
	s_mov_b32 m0, s47
	v_lshl_add_u64 v[158:159], s[22:23], 0, v[136:137]
	global_load_lds_dwordx4 v160, s[22:23]
	s_add_i32 m0, s47, 0x2000
	s_nop 0
	global_load_lds_dwordx4 v136, s[22:23]
	s_barrier
	s_waitcnt lgkmcnt(0)
	v_mfma_f32_16x16x32_bf16 v[120:123], v[230:233], v[178:181], v[120:123]
	v_mfma_f32_16x16x32_bf16 v[112:115], v[238:241], v[178:181], v[112:115]
	v_mfma_f32_16x16x32_bf16 v[104:107], v[230:233], v[186:189], v[104:107]
	v_mfma_f32_16x16x32_bf16 v[96:99], v[238:241], v[186:189], v[96:99]
	v_mfma_f32_16x16x32_bf16 v[88:91], v[230:233], v[194:197], v[88:91]
	v_mfma_f32_16x16x32_bf16 v[80:83], v[238:241], v[194:197], v[80:83]
	v_mfma_f32_16x16x32_bf16 v[72:75], v[230:233], v[222:225], v[72:75]
	v_mfma_f32_16x16x32_bf16 v[64:67], v[238:241], v[222:225], v[64:67]
	v_mfma_f32_16x16x32_bf16 v[120:123], v[234:237], v[182:185], v[120:123]
	v_mfma_f32_16x16x32_bf16 v[112:115], v[242:245], v[182:185], v[112:115]
	v_mfma_f32_16x16x32_bf16 v[104:107], v[234:237], v[190:193], v[104:107]
	v_mfma_f32_16x16x32_bf16 v[96:99], v[242:245], v[190:193], v[96:99]
	v_mfma_f32_16x16x32_bf16 v[88:91], v[234:237], v[218:221], v[88:91]
	v_mfma_f32_16x16x32_bf16 v[80:83], v[242:245], v[218:221], v[80:83]
	v_mfma_f32_16x16x32_bf16 v[72:75], v[234:237], v[226:229], v[72:75]
	v_mfma_f32_16x16x32_bf16 v[64:67], v[242:245], v[226:229], v[64:67]
	s_mov_b32 m0, s34
	v_lshl_add_u64 v[214:215], s[24:25], 0, v[140:141]
	s_barrier
; #define PG8_STAGE(bufoff, gbase, voff) do { _Pragma("unroll") for (int _i = 0; _i < 2; ++_i) \
;         __builtin_amdgcn_global_load_lds((const unsigned*)((const char*)(gbase) + (voff)[_i]), (LAS unsigned*)(lds + (bufoff) + ldsw + _i * 8192), 16, 0, 0); } while (0)
; #define PG8_LDA(dst, b, h) do { _Pragma("unroll") for (int m = 0; m < 4; ++m) _Pragma("unroll") for (int k = 0; k < 2; ++k) dst[m][k] = *(const LAS bf16x8*)(lds + PG8_SA(b, h) + aoff + m * 2048 + k * 1024); } while (0)
; #define PG8_LDB(dst, b, h) do { _Pragma("unroll") for (int n = 0; n < 2; ++n) _Pragma("unroll") for (int k = 0; k < 2; ++k) dst[n][k] = *(const LAS bf16x8*)(lds + PG8_SB(b, h) + boff + n * 2048 + k * 1024); } while (0)
; #define PG8_MMA(ai, bj, At, Bt) do { __builtin_amdgcn_s_setprio(1); _Pragma("unroll") for (int m = 0; m < 4; ++m) _Pragma("unroll") for (int n = 0; n < 2; ++n) _Pragma("unroll") for (int k = 0; k < 2; ++k) \
;         acc[ai][bj][m][n] = __builtin_amdgcn_mfma_f32_16x16x32_bf16(Bt[n][k], At[m][k], acc[ai][bj][m][n], 0, 0, 0); __builtin_amdgcn_s_setprio(0); } while (0)
; #define PG8_WAIT_V(n) asm volatile("s_waitcnt vmcnt(" #n ")" ::: "memory")
; #define PG8_WAIT_L(n) asm volatile("s_waitcnt lgkmcnt(" #n ")" ::: "memory")
; #define PG8_BAR __builtin_amdgcn_s_barrier()
; #define PG8_SCHED __builtin_amdgcn_sched_barrier(0)
; template <class Epi>
; DEV void gemm_phase(LAS unsigned char* lds, const Gemm g, const StaticOrder& S, const Epi& E) {
;     ...
;             PG8_LDB(B1, 0, 1); PG8_STAGE(PG8_SB(0, 0), b2, voffB);
;             PG8_BAR; PG8_WAIT_L(0); PG8_MMA(0, 1, At, B1); PG8_BAR;
;             PG8_LDA(At, 0, 1); PG8_STAGE(PG8_SA(0, 0), a2, voffA);
;             PG8_BAR; PG8_WAIT_L(0); PG8_MMA(1, 0, At, B0); PG8_BAR; PG8_SCHED;
;             PG8_STAGE(PG8_SB(0, 1), b2 + hstep, voffB);
;             PG8_WAIT_V(6); PG8_BAR; PG8_MMA(1, 1, At, B1); PG8_BAR;
;             PG8_LDB(B0, 1, 0); PG8_SCHED; PG8_LDA(At, 1, 0); PG8_STAGE(PG8_SA(0, 1), a2 + hstep, voffA);
;             PG8_WAIT_L(8); PG8_BAR; PG8_WAIT_L(0); PG8_MMA(0, 0, At, B0); PG8_BAR; PG8_SCHED;
;             PG8_LDB(B1, 1, 1); PG8_STAGE(PG8_SB(1, 0), b3, voffB);
;             PG8_BAR; PG8_WAIT_L(0); PG8_MMA(0, 1, At, B1); PG8_BAR;
;             PG8_LDA(At, 1, 1); PG8_STAGE(PG8_SA(1, 0), a3, voffA);
	ds_read_b128 v[178:181], v167 offset:16384
	ds_read_b128 v[182:185], v167 offset:17408
	ds_read_b128 v[186:189], v167 offset:18432
	ds_read_b128 v[190:193], v167 offset:19456
	ds_read_b128 v[194:197], v167 offset:20480
	ds_read_b128 v[218:221], v167 offset:21504
	ds_read_b128 v[222:225], v167 offset:22528
	ds_read_b128 v[226:229], v167 offset:23552
	global_load_lds_dwordx4 v140, s[24:25]
	v_lshl_add_u64 v[216:217], s[24:25], 0, v[138:139]
	s_mov_b32 m0, s35
	s_nop 0
	global_load_lds_dwordx4 v138, s[24:25]
	s_barrier
	s_waitcnt lgkmcnt(0)
	v_mfma_f32_16x16x32_bf16 v[60:63], v[128:131], v[178:181], v[60:63]
	v_mfma_f32_16x16x32_bf16 v[52:55], v[150:153], v[178:181], v[52:55]
	v_mfma_f32_16x16x32_bf16 v[44:47], v[128:131], v[186:189], v[44:47]
	v_mfma_f32_16x16x32_bf16 v[36:39], v[150:153], v[186:189], v[36:39]
	v_mfma_f32_16x16x32_bf16 v[28:31], v[128:131], v[194:197], v[28:31]
	v_mfma_f32_16x16x32_bf16 v[20:23], v[150:153], v[194:197], v[20:23]
	v_mfma_f32_16x16x32_bf16 v[12:15], v[128:131], v[222:225], v[12:15]
	v_mfma_f32_16x16x32_bf16 v[4:7], v[150:153], v[222:225], v[4:7]
	v_mfma_f32_16x16x32_bf16 v[60:63], v[132:135], v[182:185], v[60:63]
	v_mfma_f32_16x16x32_bf16 v[52:55], v[174:177], v[182:185], v[52:55]
	v_mfma_f32_16x16x32_bf16 v[44:47], v[132:135], v[190:193], v[44:47]
	v_mfma_f32_16x16x32_bf16 v[36:39], v[174:177], v[190:193], v[36:39]
	v_mfma_f32_16x16x32_bf16 v[28:31], v[132:135], v[218:221], v[28:31]
	v_mfma_f32_16x16x32_bf16 v[20:23], v[174:177], v[218:221], v[20:23]
	v_mfma_f32_16x16x32_bf16 v[12:15], v[132:135], v[226:229], v[12:15]
	v_mfma_f32_16x16x32_bf16 v[4:7], v[174:177], v[226:229], v[4:7]
	s_barrier
	s_add_u32 s48, s22, 0x80000
	s_addc_u32 s49, s23, 0
	s_add_i32 s47, s50, s30
	s_mov_b32 m0, s47
	s_nop 0
	global_load_lds_dwordx4 v160, s[48:49]
	s_add_i32 m0, s47, 0x2000
	s_nop 0
	global_load_lds_dwordx4 v136, s[48:49]
	s_waitcnt vmcnt(6)
	s_barrier
	v_mfma_f32_16x16x32_bf16 v[56:59], v[230:233], v[178:181], v[56:59]
	v_mfma_f32_16x16x32_bf16 v[48:51], v[238:241], v[178:181], v[48:51]
	v_mfma_f32_16x16x32_bf16 v[40:43], v[230:233], v[186:189], v[40:43]
	v_mfma_f32_16x16x32_bf16 v[32:35], v[238:241], v[186:189], v[32:35]
	v_mfma_f32_16x16x32_bf16 v[24:27], v[230:233], v[194:197], v[24:27]
	v_mfma_f32_16x16x32_bf16 v[16:19], v[238:241], v[194:197], v[16:19]
	v_mfma_f32_16x16x32_bf16 v[8:11], v[230:233], v[222:225], v[8:11]
	v_mfma_f32_16x16x32_bf16 v[0:3], v[238:241], v[222:225], v[0:3]
	v_mfma_f32_16x16x32_bf16 v[56:59], v[234:237], v[182:185], v[56:59]
	v_mfma_f32_16x16x32_bf16 v[48:51], v[242:245], v[182:185], v[48:51]
	v_mfma_f32_16x16x32_bf16 v[40:43], v[234:237], v[190:193], v[40:43]
	v_mfma_f32_16x16x32_bf16 v[32:35], v[242:245], v[190:193], v[32:35]
	v_mfma_f32_16x16x32_bf16 v[24:27], v[234:237], v[218:221], v[24:27]
	v_mfma_f32_16x16x32_bf16 v[16:19], v[242:245], v[218:221], v[16:19]
	v_mfma_f32_16x16x32_bf16 v[8:11], v[234:237], v[226:229], v[8:11]
	v_mfma_f32_16x16x32_bf16 v[0:3], v[242:245], v[226:229], v[0:3]
	s_add_i32 s47, 0, 0x18000
	s_barrier
	ds_read_b128 v[128:131], v148 offset:32768
	ds_read_b128 v[132:135], v148 offset:33792
	ds_read_b128 v[150:153], v148 offset:34816
	ds_read_b128 v[174:177], v148 offset:35840
	s_add_u32 s24, s24, 0x80000
	s_addc_u32 s25, s25, 0
	s_mov_b32 m0, s36
	ds_read_b128 v[178:181], v167 offset:32768
	ds_read_b128 v[182:185], v167 offset:33792
	ds_read_b128 v[186:189], v167 offset:34816
	ds_read_b128 v[190:193], v167 offset:35840
	ds_read_b128 v[194:197], v167 offset:36864
	ds_read_b128 v[218:221], v167 offset:37888
	ds_read_b128 v[222:225], v167 offset:38912
	ds_read_b128 v[226:229], v167 offset:39936
	global_load_lds_dwordx4 v140, s[24:25]
	s_mov_b32 m0, s37
	s_nop 0
	global_load_lds_dwordx4 v138, s[24:25]
	s_waitcnt lgkmcnt(8)
	s_barrier
	s_waitcnt lgkmcnt(0)
	v_mfma_f32_16x16x32_bf16 v[124:127], v[128:131], v[178:181], v[124:127]
	v_mfma_f32_16x16x32_bf16 v[116:119], v[150:153], v[178:181], v[116:119]
	v_mfma_f32_16x16x32_bf16 v[108:111], v[128:131], v[186:189], v[108:111]
	v_mfma_f32_16x16x32_bf16 v[100:103], v[150:153], v[186:189], v[100:103]
	v_mfma_f32_16x16x32_bf16 v[92:95], v[128:131], v[194:197], v[92:95]
	v_mfma_f32_16x16x32_bf16 v[84:87], v[150:153], v[194:197], v[84:87]
	v_mfma_f32_16x16x32_bf16 v[76:79], v[128:131], v[222:225], v[76:79]
	v_mfma_f32_16x16x32_bf16 v[68:71], v[150:153], v[222:225], v[68:71]
	v_mfma_f32_16x16x32_bf16 v[124:127], v[132:135], v[182:185], v[124:127]
	v_mfma_f32_16x16x32_bf16 v[116:119], v[174:177], v[182:185], v[116:119]
	v_mfma_f32_16x16x32_bf16 v[108:111], v[132:135], v[190:193], v[108:111]
	v_mfma_f32_16x16x32_bf16 v[100:103], v[174:177], v[190:193], v[100:103]
	v_mfma_f32_16x16x32_bf16 v[92:95], v[132:135], v[218:221], v[92:95]
	v_mfma_f32_16x16x32_bf16 v[84:87], v[174:177], v[218:221], v[84:87]
	v_mfma_f32_16x16x32_bf16 v[76:79], v[132:135], v[226:229], v[76:79]
	v_mfma_f32_16x16x32_bf16 v[68:71], v[174:177], v[226:229], v[68:71]
	s_barrier
	s_add_i32 s24, 0, 0x1c000
	s_add_i32 s25, s47, s30
	v_lshl_add_u64 v[146:147], v[146:147], 0, s[2:3]
	s_mov_b32 m0, s25
	ds_read_b128 v[230:233], v148 offset:49152
	ds_read_b128 v[234:237], v148 offset:50176
	ds_read_b128 v[238:241], v148 offset:51200
	ds_read_b128 v[242:245], v148 offset:52224
	global_load_lds_dwordx4 v[146:147], off
	v_lshl_add_u64 v[146:147], v[158:159], 0, s[2:3]
	s_add_i32 m0, s25, 0x2000
	s_nop 0
	global_load_lds_dwordx4 v[146:147], off
	s_barrier
; #define PG8_STAGE(bufoff, gbase, voff) do { _Pragma("unroll") for (int _i = 0; _i < 2; ++_i) \
;         __builtin_amdgcn_global_load_lds((const unsigned*)((const char*)(gbase) + (voff)[_i]), (LAS unsigned*)(lds + (bufoff) + ldsw + _i * 8192), 16, 0, 0); } while (0)
; #define PG8_LDA(dst, b, h) do { _Pragma("unroll") for (int m = 0; m < 4; ++m) _Pragma("unroll") for (int k = 0; k < 2; ++k) dst[m][k] = *(const LAS bf16x8*)(lds + PG8_SA(b, h) + aoff + m * 2048 + k * 1024); } while (0)
; #define PG8_MMA(ai, bj, At, Bt) do { __builtin_amdgcn_s_setprio(1); _Pragma("unroll") for (int m = 0; m < 4; ++m) _Pragma("unroll") for (int n = 0; n < 2; ++n) _Pragma("unroll") for (int k = 0; k < 2; ++k) \
;         acc[ai][bj][m][n] = __builtin_amdgcn_mfma_f32_16x16x32_bf16(Bt[n][k], At[m][k], acc[ai][bj][m][n], 0, 0, 0); __builtin_amdgcn_s_setprio(0); } while (0)
; #define PG8_WAIT_V(n) asm volatile("s_waitcnt vmcnt(" #n ")" ::: "memory")
; #define PG8_WAIT_L(n) asm volatile("s_waitcnt lgkmcnt(" #n ")" ::: "memory")
; #define PG8_BAR __builtin_amdgcn_s_barrier()
; #define PG8_SCHED __builtin_amdgcn_sched_barrier(0)
; template <class Epi>
; DEV void gemm_phase(LAS unsigned char* lds, const Gemm g, const StaticOrder& S, const Epi& E) {
;     ...
;             PG8_BAR; PG8_WAIT_L(0); PG8_MMA(0, 1, At, B1); PG8_BAR;
;             PG8_LDA(At, 1, 1); PG8_STAGE(PG8_SA(1, 0), a3, voffA);
;             PG8_BAR; PG8_WAIT_L(0); PG8_MMA(1, 0, At, B0); PG8_BAR; PG8_SCHED;
;             PG8_STAGE(PG8_SB(1, 1), b3 + hstep, voffB);
;             PG8_WAIT_V(6); PG8_BAR; PG8_MMA(1, 1, At, B1); PG8_BAR;
;         }
	s_waitcnt lgkmcnt(0)
	v_mfma_f32_16x16x32_bf16 v[120:123], v[230:233], v[178:181], v[120:123]
	v_mfma_f32_16x16x32_bf16 v[112:115], v[238:241], v[178:181], v[112:115]
	v_mfma_f32_16x16x32_bf16 v[104:107], v[230:233], v[186:189], v[104:107]
	v_mfma_f32_16x16x32_bf16 v[96:99], v[238:241], v[186:189], v[96:99]
	v_mfma_f32_16x16x32_bf16 v[88:91], v[230:233], v[194:197], v[88:91]
	v_mfma_f32_16x16x32_bf16 v[80:83], v[238:241], v[194:197], v[80:83]
	v_mfma_f32_16x16x32_bf16 v[72:75], v[230:233], v[222:225], v[72:75]
	v_mfma_f32_16x16x32_bf16 v[64:67], v[238:241], v[222:225], v[64:67]
	v_mfma_f32_16x16x32_bf16 v[120:123], v[234:237], v[182:185], v[120:123]
	v_mfma_f32_16x16x32_bf16 v[112:115], v[242:245], v[182:185], v[112:115]
	v_mfma_f32_16x16x32_bf16 v[104:107], v[234:237], v[190:193], v[104:107]
	v_mfma_f32_16x16x32_bf16 v[96:99], v[242:245], v[190:193], v[96:99]
	v_mfma_f32_16x16x32_bf16 v[88:91], v[234:237], v[218:221], v[88:91]
	v_mfma_f32_16x16x32_bf16 v[80:83], v[242:245], v[218:221], v[80:83]
	v_mfma_f32_16x16x32_bf16 v[72:75], v[234:237], v[226:229], v[72:75]
	v_mfma_f32_16x16x32_bf16 v[64:67], v[242:245], v[226:229], v[64:67]
	s_mov_b32 m0, s38
	v_lshl_add_u64 v[146:147], v[214:215], 0, s[2:3]
	s_barrier
	ds_read_b128 v[178:181], v167 offset:49152
	ds_read_b128 v[182:185], v167 offset:50176
	ds_read_b128 v[186:189], v167 offset:51200
	ds_read_b128 v[190:193], v167 offset:52224
	ds_read_b128 v[194:197], v167 offset:53248
	ds_read_b128 v[218:221], v167 offset:54272
	ds_read_b128 v[222:225], v167 offset:55296
	ds_read_b128 v[226:229], v167 offset:56320
	global_load_lds_dwordx4 v[146:147], off
	v_lshl_add_u64 v[146:147], v[216:217], 0, s[2:3]
	s_mov_b32 m0, s39
	s_nop 0
	global_load_lds_dwordx4 v[146:147], off
	s_barrier
	s_waitcnt lgkmcnt(0)
	v_mfma_f32_16x16x32_bf16 v[60:63], v[128:131], v[178:181], v[60:63]
	v_mfma_f32_16x16x32_bf16 v[52:55], v[150:153], v[178:181], v[52:55]
	v_mfma_f32_16x16x32_bf16 v[44:47], v[128:131], v[186:189], v[44:47]
	v_mfma_f32_16x16x32_bf16 v[36:39], v[150:153], v[186:189], v[36:39]
	v_mfma_f32_16x16x32_bf16 v[28:31], v[128:131], v[194:197], v[28:31]
	v_mfma_f32_16x16x32_bf16 v[20:23], v[150:153], v[194:197], v[20:23]
	v_mfma_f32_16x16x32_bf16 v[12:15], v[128:131], v[222:225], v[12:15]
	v_mfma_f32_16x16x32_bf16 v[4:7], v[150:153], v[222:225], v[4:7]
	v_mfma_f32_16x16x32_bf16 v[60:63], v[132:135], v[182:185], v[60:63]
	v_mfma_f32_16x16x32_bf16 v[52:55], v[174:177], v[182:185], v[52:55]
	v_mfma_f32_16x16x32_bf16 v[44:47], v[132:135], v[190:193], v[44:47]
	v_mfma_f32_16x16x32_bf16 v[36:39], v[174:177], v[190:193], v[36:39]
	v_mfma_f32_16x16x32_bf16 v[28:31], v[132:135], v[218:221], v[28:31]
	v_mfma_f32_16x16x32_bf16 v[20:23], v[174:177], v[218:221], v[20:23]
	v_mfma_f32_16x16x32_bf16 v[12:15], v[132:135], v[226:229], v[12:15]
	v_mfma_f32_16x16x32_bf16 v[4:7], v[174:177], v[226:229], v[4:7]
	s_barrier
	s_add_u32 s22, s22, 0x80080
	s_addc_u32 s23, s23, 0
	s_add_i32 s24, s24, s30
	s_mov_b32 m0, s24
	s_nop 0
	global_load_lds_dwordx4 v160, s[22:23]
	s_add_i32 m0, s24, 0x2000
	s_nop 0
	global_load_lds_dwordx4 v136, s[22:23]
	s_waitcnt vmcnt(6)
	s_barrier
	v_mfma_f32_16x16x32_bf16 v[56:59], v[230:233], v[178:181], v[56:59]
	v_mfma_f32_16x16x32_bf16 v[48:51], v[238:241], v[178:181], v[48:51]
	v_mfma_f32_16x16x32_bf16 v[40:43], v[230:233], v[186:189], v[40:43]
	v_mfma_f32_16x16x32_bf16 v[32:35], v[238:241], v[186:189], v[32:35]
	v_mfma_f32_16x16x32_bf16 v[24:27], v[230:233], v[194:197], v[24:27]
	v_mfma_f32_16x16x32_bf16 v[16:19], v[238:241], v[194:197], v[16:19]
	v_mfma_f32_16x16x32_bf16 v[8:11], v[230:233], v[222:225], v[8:11]
	v_mfma_f32_16x16x32_bf16 v[0:3], v[238:241], v[222:225], v[0:3]
	v_mfma_f32_16x16x32_bf16 v[56:59], v[234:237], v[182:185], v[56:59]
	v_mfma_f32_16x16x32_bf16 v[48:51], v[242:245], v[182:185], v[48:51]
	v_mfma_f32_16x16x32_bf16 v[40:43], v[234:237], v[190:193], v[40:43]
	v_mfma_f32_16x16x32_bf16 v[32:35], v[242:245], v[190:193], v[32:35]
	v_mfma_f32_16x16x32_bf16 v[24:27], v[234:237], v[218:221], v[24:27]
	v_mfma_f32_16x16x32_bf16 v[16:19], v[242:245], v[218:221], v[16:19]
	v_mfma_f32_16x16x32_bf16 v[8:11], v[234:237], v[226:229], v[8:11]
	v_mfma_f32_16x16x32_bf16 v[0:3], v[242:245], v[226:229], v[0:3]
	s_add_i32 s46, s46, 2
	s_add_u32 s20, s20, 0x100
	s_addc_u32 s21, s21, 0
	s_add_u32 s44, s44, 0x100
	s_addc_u32 s45, s45, 0
	s_cmp_gt_u32 s46, 29
	s_barrier
	s_cbranch_scc0 .LBB0_755
;     DEV void operator()(AccRef acc, const pg8::Unit& u, int wr, int wc, int fr, int fq) const { store_bf16_tile<0, false>(acc, O, ld, u.pm * 256 + wr * 64 + fr, u.pn * 256 + wc * 32 + 4 * fq, ss); }
; DEV float rowscale(const float* ss, int row) { const f32x4 a = *(const f32x4*)(ss + (size_t)row * 8), b = *(const f32x4*)(ss + (size_t)row * 8 + 4);
;     return rsqrtf(((a[0] + a[1]) + (a[2] + a[3]) + (b[0] + b[1]) + (b[2] + b[3])) * (1.0f / 2048.0f) + EPS); }
;     DEV void operator()(AccRef acc, const pg8::Unit& u, int wr, int wc, int fr, int fq) const {
;         const int row0 = u.pm * 256 + wr * 64 + fr, col0 = u.pn * 128 + wc * 32 + 8 * fq;
;         float rsv[2][4];
; #pragma unroll
;         for (int ai = 0; ai < 2; ++ai)
; #pragma unroll
;             for (int m = 0; m < 4; ++m) rsv[ai][m] = rowscale(ss, row0 + ai * 128 + m * 16);
; #pragma unroll
;         for (int ai = 0; ai < 2; ++ai)
; #pragma unroll
;             for (int m = 0; m < 4; ++m) { u16* rowp = O + (size_t)(row0 + ai * 128 + m * 16) * 5632 + col0; const float rs = rsv[ai][m]; f32x4 r[2];
; #pragma unroll
;                 for (int n = 0; n < 2; ++n) { const f32x4 g = acc[ai][0][m][n] * rs, uu = acc[ai][1][m][n] * rs;
	v_lshl_add_u32 v186, s4, 8, v149
	v_ashrrev_i32_e32 v187, 31, v186
	v_lshlrev_b64 v[146:147], 5, v[186:187]
	v_lshl_add_u64 v[146:147], s[8:9], 0, v[146:147]
	v_add_co_u32_e32 v158, vcc, 0x1000, v146
	global_load_dwordx4 v[218:221], v[146:147], off
	global_load_dwordx4 v[222:225], v[146:147], off offset:16
	v_addc_co_u32_e32 v159, vcc, 0, v147, vcc
	global_load_dwordx4 v[174:177], v[146:147], off offset:512
	global_load_dwordx4 v[230:233], v[146:147], off offset:528
	global_load_dwordx4 v[234:237], v[146:147], off offset:1024
	global_load_dwordx4 v[238:241], v[146:147], off offset:1040
	global_load_dwordx4 v[242:245], v[146:147], off offset:1536
	global_load_dwordx4 v[246:249], v[146:147], off offset:1552
	global_load_dwordx4 v[190:193], v[158:159], off
	global_load_dwordx4 v[194:197], v[158:159], off offset:16
	global_load_dwordx4 v[214:217], v[158:159], off offset:512
	global_load_dwordx4 v[132:135], v[158:159], off offset:528
	global_load_dwordx4 v[150:153], v[158:159], off offset:1024
	global_load_dwordx4 v[128:131], v[158:159], off offset:1040
	global_load_dwordx4 v[226:229], v[158:159], off offset:1536
	global_load_dwordx4 v[180:183], v[158:159], off offset:1552
	s_mov_b32 s12, 0x3a000000
	s_mov_b64 s[22:23], s[18:19]
	s_mov_b64 s[20:21], s[16:17]
	s_movk_i32 s11, 0x2c00
	v_readlane_b32 s4, v250, 11
	v_readlane_b32 s5, v250, 12
	s_waitcnt vmcnt(14)
	v_add_f32_e32 v218, v218, v219
	v_add_f32_e32 v220, v220, v221
	v_add_f32_e32 v222, v222, v223
	v_add_f32_e32 v224, v224, v225
	v_add_f32_e32 v218, v218, v220
	v_add_f32_e32 v218, v218, v222
	v_add_f32_e32 v218, v218, v224
	v_fmamk_f32 v218, v218, 0x3a000000, v199
	v_rsq_f32_e32 v184, v218
	s_waitcnt vmcnt(12)
	v_add_f32_e32 v174, v174, v175
	v_add_f32_e32 v176, v176, v177
	v_add_f32_e32 v230, v230, v231
	v_add_f32_e32 v232, v232, v233
	v_add_f32_e32 v174, v174, v176
	v_add_f32_e32 v174, v174, v230
	v_add_f32_e32 v174, v174, v232
	v_fmamk_f32 v174, v174, 0x3a000000, v199
	v_rsq_f32_e32 v176, v174
	v_pk_mul_f32 v[124:125], v[124:125], v[184:185] op_sel_hi:[1,0]
	v_pk_mul_f32 v[120:121], v[120:121], v[184:185] op_sel_hi:[1,0]
	v_pk_mul_f32 v[122:123], v[122:123], v[184:185] op_sel_hi:[1,0]
	v_pk_mul_f32 v[116:117], v[116:117], v[184:185] op_sel_hi:[1,0]
	v_pk_mul_f32 v[112:113], v[112:113], v[184:185] op_sel_hi:[1,0]
	v_pk_mul_f32 v[114:115], v[114:115], v[184:185] op_sel_hi:[1,0]
	s_waitcnt vmcnt(10)
	v_add_f32_e32 v234, v234, v235
	v_add_f32_e32 v236, v236, v237
	v_add_f32_e32 v238, v238, v239
	v_add_f32_e32 v240, v240, v241
	v_add_f32_e32 v234, v234, v236
	v_add_f32_e32 v234, v234, v238
	v_add_f32_e32 v234, v234, v240
	v_fmamk_f32 v234, v234, 0x3a000000, v199
	v_rsq_f32_e32 v178, v234
	v_pk_mul_f32 v[108:109], v[108:109], v[176:177] op_sel_hi:[1,0]
	v_pk_mul_f32 v[104:105], v[104:105], v[176:177] op_sel_hi:[1,0]
	v_pk_mul_f32 v[106:107], v[106:107], v[176:177] op_sel_hi:[1,0]
	v_pk_mul_f32 v[100:101], v[100:101], v[176:177] op_sel_hi:[1,0]
	v_pk_mul_f32 v[96:97], v[96:97], v[176:177] op_sel_hi:[1,0]
	v_pk_mul_f32 v[98:99], v[98:99], v[176:177] op_sel_hi:[1,0]
	s_waitcnt vmcnt(8)
	v_add_f32_e32 v242, v242, v243
	v_add_f32_e32 v244, v244, v245
	v_add_f32_e32 v246, v246, v247
	v_add_f32_e32 v248, v248, v249
	v_add_f32_e32 v242, v242, v244
	v_add_f32_e32 v242, v242, v246
	v_add_f32_e32 v242, v242, v248
	v_fmamk_f32 v242, v242, 0x3a000000, v199
	v_rsq_f32_e32 v154, v242
	v_pk_mul_f32 v[92:93], v[92:93], v[178:179] op_sel_hi:[1,0]
	v_pk_mul_f32 v[88:89], v[88:89], v[178:179] op_sel_hi:[1,0]
	v_pk_mul_f32 v[90:91], v[90:91], v[178:179] op_sel_hi:[1,0]
	v_pk_mul_f32 v[84:85], v[84:85], v[178:179] op_sel_hi:[1,0]
	v_pk_mul_f32 v[80:81], v[80:81], v[178:179] op_sel_hi:[1,0]
	v_pk_mul_f32 v[82:83], v[82:83], v[178:179] op_sel_hi:[1,0]
	s_waitcnt vmcnt(6)
	v_add_f32_e32 v190, v190, v191
	v_add_f32_e32 v192, v192, v193
	v_add_f32_e32 v194, v194, v195
	v_add_f32_e32 v196, v196, v197
	v_add_f32_e32 v190, v190, v192
	v_add_f32_e32 v190, v190, v194
	v_add_f32_e32 v190, v190, v196
	v_fmamk_f32 v190, v190, 0x3a000000, v199
	v_rsq_f32_e32 v156, v190
	v_pk_mul_f32 v[76:77], v[76:77], v[154:155] op_sel_hi:[1,0]
	v_pk_mul_f32 v[72:73], v[72:73], v[154:155] op_sel_hi:[1,0]
	v_pk_mul_f32 v[74:75], v[74:75], v[154:155] op_sel_hi:[1,0]
	v_pk_mul_f32 v[68:69], v[68:69], v[154:155] op_sel_hi:[1,0]
	v_pk_mul_f32 v[64:65], v[64:65], v[154:155] op_sel_hi:[1,0]
	v_pk_mul_f32 v[66:67], v[66:67], v[154:155] op_sel_hi:[1,0]
	s_waitcnt vmcnt(4)
	v_add_f32_e32 v214, v214, v215
	v_add_f32_e32 v216, v216, v217
	v_add_f32_e32 v132, v132, v133
	v_add_f32_e32 v134, v134, v135
	v_add_f32_e32 v214, v214, v216
	v_add_f32_e32 v214, v214, v132
	v_add_f32_e32 v214, v214, v134
	v_fmamk_f32 v214, v214, 0x3a000000, v199
	v_rsq_f32_e32 v148, v214
	v_pk_mul_f32 v[60:61], v[60:61], v[156:157] op_sel_hi:[1,0]
	v_pk_mul_f32 v[56:57], v[56:57], v[156:157] op_sel_hi:[1,0]
	v_pk_mul_f32 v[58:59], v[58:59], v[156:157] op_sel_hi:[1,0]
	v_pk_mul_f32 v[52:53], v[52:53], v[156:157] op_sel_hi:[1,0]
	v_pk_mul_f32 v[48:49], v[48:49], v[156:157] op_sel_hi:[1,0]
	v_pk_mul_f32 v[50:51], v[50:51], v[156:157] op_sel_hi:[1,0]
	s_waitcnt vmcnt(2)
	v_add_f32_e32 v150, v150, v151
	v_add_f32_e32 v152, v152, v153
	v_add_f32_e32 v128, v128, v129
	v_add_f32_e32 v130, v130, v131
	v_add_f32_e32 v150, v150, v152
	v_add_f32_e32 v150, v150, v128
	v_add_f32_e32 v150, v150, v130
	v_fmamk_f32 v150, v150, 0x3a000000, v199
	v_rsq_f32_e32 v130, v150
	v_pk_mul_f32 v[44:45], v[44:45], v[148:149] op_sel_hi:[1,0]
	v_pk_mul_f32 v[40:41], v[40:41], v[148:149] op_sel_hi:[1,0]
	v_pk_mul_f32 v[42:43], v[42:43], v[148:149] op_sel_hi:[1,0]
	v_pk_mul_f32 v[36:37], v[36:37], v[148:149] op_sel_hi:[1,0]
	v_pk_mul_f32 v[32:33], v[32:33], v[148:149] op_sel_hi:[1,0]
	v_pk_mul_f32 v[34:35], v[34:35], v[148:149] op_sel_hi:[1,0]
	s_waitcnt vmcnt(0)
; DEV bf16x8 pack8(f32x4 a, f32x4 b) { u32x4 w; w.x = cvt_pk_bf16(a[0], a[1]); w.y = cvt_pk_bf16(a[2], a[3]); w.z = cvt_pk_bf16(b[0], b[1]); w.w = cvt_pk_bf16(b[2], b[3]); return __builtin_bit_cast(bf16x8, w); }
; DEV float siluf(float x) { return x * __builtin_amdgcn_rcpf(1.0f + __builtin_amdgcn_exp2f(x * -1.4426950408889634f)); }
;     DEV void operator()(AccRef acc, const pg8::Unit& u, int wr, int wc, int fr, int fq) const {
;     ...
;             for (int m = 0; m < 4; ++m) { u16* rowp = O + (size_t)(row0 + ai * 128 + m * 16) * 5632 + col0; const float rs = rsv[ai][m]; f32x4 r[2];
; #pragma unroll
;                 for (int n = 0; n < 2; ++n) { const f32x4 g = acc[ai][0][m][n] * rs, uu = acc[ai][1][m][n] * rs;
; #pragma unroll
;                     for (int e = 0; e < 4; ++e) r[n][e] = siluf(g[e]) * uu[e]; }
;                 *(u32x4*)rowp = __builtin_bit_cast(u32x4, pack8(r[0], r[1])); }
	v_add_f32_e32 v226, v226, v227
	v_add_f32_e32 v228, v228, v229
	v_add_f32_e32 v180, v180, v181
	v_add_f32_e32 v182, v182, v183
	v_add_f32_e32 v226, v226, v228
	v_add_f32_e32 v226, v226, v180
	v_add_f32_e32 v226, v226, v182
	v_fmamk_f32 v226, v226, 0x3a000000, v199
	v_rsq_f32_e32 v128, v226
	v_pk_mul_f32 v[28:29], v[28:29], v[130:131] op_sel_hi:[1,0]
	v_or_b32_e32 v182, 16, v186
	v_ashrrev_i32_e32 v183, 31, v182
	v_or_b32_e32 v180, 32, v186
	v_ashrrev_i32_e32 v181, 31, v180
	v_or_b32_e32 v174, 48, v186
	v_ashrrev_i32_e32 v175, 31, v174
	v_add_u32_e32 v158, 0x80, v186
	v_ashrrev_i32_e32 v159, 31, v158
	v_add_u32_e32 v152, 0x90, v186
	v_ashrrev_i32_e32 v153, 31, v152
	v_add_u32_e32 v150, 0xa0, v186
	v_ashrrev_i32_e32 v151, 31, v150
	v_add_u32_e32 v146, 0xb0, v186
	v_ashrrev_i32_e32 v147, 31, v146
	v_lshl_or_b32 v134, s42, 7, v157
	v_ashrrev_i32_e32 v135, 31, v134
	s_mov_b32 s42, s10
	v_mul_f32_e32 v129, 0xbfb8aa3b, v124
	v_exp_f32_e32 v129, v129
	v_mov_b64_e32 v[132:133], s[4:5]
	v_mad_i64_i32 v[186:187], s[4:5], v186, s11, v[132:133]
	v_add_f32_e32 v129, 1.0, v129
	v_rcp_f32_e32 v188, v129
	v_mul_f32_e32 v129, 0xbfb8aa3b, v125
	v_exp_f32_e32 v129, v129
	v_pk_mul_f32 v[24:25], v[24:25], v[130:131] op_sel_hi:[1,0]
	v_pk_mul_f32 v[26:27], v[26:27], v[130:131] op_sel_hi:[1,0]
	v_pk_mul_f32 v[20:21], v[20:21], v[130:131] op_sel_hi:[1,0]
	v_add_f32_e32 v129, 1.0, v129
	v_rcp_f32_e32 v189, v129
	v_pk_mul_f32 v[16:17], v[16:17], v[130:131] op_sel_hi:[1,0]
	v_pk_mul_f32 v[18:19], v[18:19], v[130:131] op_sel_hi:[1,0]
	v_pk_mul_f32 v[12:13], v[12:13], v[128:129] op_sel_hi:[1,0]
	v_pk_mul_f32 v[124:125], v[124:125], v[188:189]
	v_pk_mul_f32 v[8:9], v[8:9], v[128:129] op_sel_hi:[1,0]
	v_pk_mul_f32 v[120:121], v[120:121], v[124:125]
	v_pk_mul_f32 v[124:125], v[126:127], v[184:185] op_sel_hi:[1,0]
	v_pk_mul_f32 v[10:11], v[10:11], v[128:129] op_sel_hi:[1,0]
	v_mul_f32_e32 v126, 0xbfb8aa3b, v124
	v_mul_f32_e32 v127, 0xbfb8aa3b, v125
	v_exp_f32_e32 v126, v126
	v_exp_f32_e32 v127, v127
	v_pk_mul_f32 v[4:5], v[4:5], v[128:129] op_sel_hi:[1,0]
	v_pk_mul_f32 v[0:1], v[0:1], v[128:129] op_sel_hi:[1,0]
	v_add_f32_e32 v126, 1.0, v126
	v_add_f32_e32 v127, 1.0, v127
	v_rcp_f32_e32 v126, v126
	v_rcp_f32_e32 v127, v127
	v_pk_mul_f32 v[2:3], v[2:3], v[128:129] op_sel_hi:[1,0]
	s_and_b64 vcc, exec, s[0:1]
	v_pk_mul_f32 v[124:125], v[124:125], v[126:127]
	s_nop 0
	v_pk_mul_f32 v[122:123], v[122:123], v[124:125]
	v_mul_f32_e32 v124, 0xbfb8aa3b, v116
	v_mul_f32_e32 v125, 0xbfb8aa3b, v117
	v_exp_f32_e32 v124, v124
	v_exp_f32_e32 v125, v125
	v_add_f32_e32 v124, 1.0, v124
	v_add_f32_e32 v125, 1.0, v125
	v_rcp_f32_e32 v124, v124
	v_rcp_f32_e32 v125, v125
	s_nop 0
	v_pk_mul_f32 v[116:117], v[116:117], v[124:125]
	s_nop 0
	v_pk_mul_f32 v[116:117], v[112:113], v[116:117]
	v_pk_mul_f32 v[112:113], v[118:119], v[184:185] op_sel_hi:[1,0]
	v_cvt_pk_bf16_f32 v116, v116, v117
	v_mul_f32_e32 v118, 0xbfb8aa3b, v112
	v_mul_f32_e32 v119, 0xbfb8aa3b, v113
	v_exp_f32_e32 v118, v118
	v_exp_f32_e32 v119, v119
	v_add_f32_e32 v118, 1.0, v118
	v_add_f32_e32 v119, 1.0, v119
	v_rcp_f32_e32 v118, v118
	v_rcp_f32_e32 v119, v119
	s_nop 0
	v_pk_mul_f32 v[112:113], v[112:113], v[118:119]
	s_nop 0
	v_pk_mul_f32 v[118:119], v[114:115], v[112:113]
	v_lshlrev_b64 v[112:113], 1, v[134:135]
	v_lshl_add_u64 v[124:125], v[186:187], 0, v[112:113]
	v_cvt_pk_bf16_f32 v114, v120, v121
	v_cvt_pk_bf16_f32 v115, v122, v123
	v_cvt_pk_bf16_f32 v117, v118, v119
	global_store_dwordx4 v[124:125], v[114:117], off
	s_nop 1
	v_mul_f32_e32 v116, 0xbfb8aa3b, v108
	v_mul_f32_e32 v117, 0xbfb8aa3b, v109
	v_exp_f32_e32 v116, v116
	v_exp_f32_e32 v117, v117
	v_mad_i64_i32 v[114:115], s[4:5], v182, s11, v[132:133]
	v_add_f32_e32 v116, 1.0, v116
	v_add_f32_e32 v117, 1.0, v117
	v_rcp_f32_e32 v116, v116
	v_rcp_f32_e32 v117, v117
	s_nop 0
	v_pk_mul_f32 v[108:109], v[108:109], v[116:117]
	s_nop 0
	v_pk_mul_f32 v[104:105], v[104:105], v[108:109]
	v_pk_mul_f32 v[108:109], v[110:111], v[176:177] op_sel_hi:[1,0]
	s_nop 0
	v_mul_f32_e32 v110, 0xbfb8aa3b, v108
	v_mul_f32_e32 v111, 0xbfb8aa3b, v109
	v_exp_f32_e32 v110, v110
	v_exp_f32_e32 v111, v111
	v_add_f32_e32 v110, 1.0, v110
	v_add_f32_e32 v111, 1.0, v111
	v_rcp_f32_e32 v110, v110
	v_rcp_f32_e32 v111, v111
	s_nop 0
	v_pk_mul_f32 v[108:109], v[108:109], v[110:111]
	s_nop 0
	v_pk_mul_f32 v[106:107], v[106:107], v[108:109]
	v_mul_f32_e32 v108, 0xbfb8aa3b, v100
	v_mul_f32_e32 v109, 0xbfb8aa3b, v101
	v_exp_f32_e32 v108, v108
	v_exp_f32_e32 v109, v109
	v_add_f32_e32 v108, 1.0, v108
	v_add_f32_e32 v109, 1.0, v109
	v_rcp_f32_e32 v108, v108
	v_rcp_f32_e32 v109, v109
	s_nop 0
	v_pk_mul_f32 v[100:101], v[100:101], v[108:109]
	s_nop 0
	v_pk_mul_f32 v[100:101], v[96:97], v[100:101]
	v_pk_mul_f32 v[96:97], v[102:103], v[176:177] op_sel_hi:[1,0]
	v_lshl_add_u64 v[108:109], v[114:115], 0, v[112:113]
	v_mul_f32_e32 v102, 0xbfb8aa3b, v96
	v_mul_f32_e32 v103, 0xbfb8aa3b, v97
	v_exp_f32_e32 v102, v102
	v_exp_f32_e32 v103, v103
	v_add_f32_e32 v102, 1.0, v102
	v_add_f32_e32 v103, 1.0, v103
	v_rcp_f32_e32 v102, v102
	v_rcp_f32_e32 v103, v103
	s_nop 0
	v_pk_mul_f32 v[96:97], v[96:97], v[102:103]
	s_nop 0
	v_pk_mul_f32 v[102:103], v[98:99], v[96:97]
	v_cvt_pk_bf16_f32 v96, v104, v105
	v_cvt_pk_bf16_f32 v97, v106, v107
	v_cvt_pk_bf16_f32 v98, v100, v101
	v_cvt_pk_bf16_f32 v99, v102, v103
	global_store_dwordx4 v[108:109], v[96:99], off
	s_nop 1
	v_mul_f32_e32 v98, 0xbfb8aa3b, v92
	v_mul_f32_e32 v99, 0xbfb8aa3b, v93
	v_exp_f32_e32 v98, v98
	v_exp_f32_e32 v99, v99
	v_mad_i64_i32 v[96:97], s[4:5], v180, s11, v[132:133]
	v_add_f32_e32 v98, 1.0, v98
	v_add_f32_e32 v99, 1.0, v99
	v_rcp_f32_e32 v98, v98
	v_rcp_f32_e32 v99, v99
; DEV bf16x8 pack8(f32x4 a, f32x4 b) { u32x4 w; w.x = cvt_pk_bf16(a[0], a[1]); w.y = cvt_pk_bf16(a[2], a[3]); w.z = cvt_pk_bf16(b[0], b[1]); w.w = cvt_pk_bf16(b[2], b[3]); return __builtin_bit_cast(bf16x8, w); }
; DEV float siluf(float x) { return x * __builtin_amdgcn_rcpf(1.0f + __builtin_amdgcn_exp2f(x * -1.4426950408889634f)); }
;     DEV void operator()(AccRef acc, const pg8::Unit& u, int wr, int wc, int fr, int fq) const {
;     ...
;             for (int m = 0; m < 4; ++m) { u16* rowp = O + (size_t)(row0 + ai * 128 + m * 16) * 5632 + col0; const float rs = rsv[ai][m]; f32x4 r[2];
; #pragma unroll
;                 for (int n = 0; n < 2; ++n) { const f32x4 g = acc[ai][0][m][n] * rs, uu = acc[ai][1][m][n] * rs;
; #pragma unroll
;                     for (int e = 0; e < 4; ++e) r[n][e] = siluf(g[e]) * uu[e]; }
;                 *(u32x4*)rowp = __builtin_bit_cast(u32x4, pack8(r[0], r[1])); }
	s_nop 0
	v_pk_mul_f32 v[92:93], v[92:93], v[98:99]
	s_nop 0
	v_pk_mul_f32 v[88:89], v[88:89], v[92:93]
	v_pk_mul_f32 v[92:93], v[94:95], v[178:179] op_sel_hi:[1,0]
	s_nop 0
	v_mul_f32_e32 v94, 0xbfb8aa3b, v92
	v_mul_f32_e32 v95, 0xbfb8aa3b, v93
	v_exp_f32_e32 v94, v94
	v_exp_f32_e32 v95, v95
	v_add_f32_e32 v94, 1.0, v94
	v_add_f32_e32 v95, 1.0, v95
	v_rcp_f32_e32 v94, v94
	v_rcp_f32_e32 v95, v95
	s_nop 0
	v_pk_mul_f32 v[92:93], v[92:93], v[94:95]
	s_nop 0
	v_pk_mul_f32 v[90:91], v[90:91], v[92:93]
	v_mul_f32_e32 v92, 0xbfb8aa3b, v84
	v_mul_f32_e32 v93, 0xbfb8aa3b, v85
	v_exp_f32_e32 v92, v92
	v_exp_f32_e32 v93, v93
	v_add_f32_e32 v92, 1.0, v92
	v_add_f32_e32 v93, 1.0, v93
	v_rcp_f32_e32 v92, v92
	v_rcp_f32_e32 v93, v93
	s_nop 0
	v_pk_mul_f32 v[84:85], v[84:85], v[92:93]
	s_nop 0
	v_pk_mul_f32 v[84:85], v[80:81], v[84:85]
	v_pk_mul_f32 v[80:81], v[86:87], v[178:179] op_sel_hi:[1,0]
	v_lshl_add_u64 v[92:93], v[96:97], 0, v[112:113]
	v_mul_f32_e32 v86, 0xbfb8aa3b, v80
	v_mul_f32_e32 v87, 0xbfb8aa3b, v81
	v_exp_f32_e32 v86, v86
	v_exp_f32_e32 v87, v87
	v_add_f32_e32 v86, 1.0, v86
	v_add_f32_e32 v87, 1.0, v87
	v_rcp_f32_e32 v86, v86
	v_rcp_f32_e32 v87, v87
	s_nop 0
	v_pk_mul_f32 v[80:81], v[80:81], v[86:87]
	s_nop 0
	v_pk_mul_f32 v[86:87], v[82:83], v[80:81]
	v_cvt_pk_bf16_f32 v80, v88, v89
	v_cvt_pk_bf16_f32 v81, v90, v91
	v_cvt_pk_bf16_f32 v82, v84, v85
	v_cvt_pk_bf16_f32 v83, v86, v87
	global_store_dwordx4 v[92:93], v[80:83], off
	s_nop 1
	v_mul_f32_e32 v82, 0xbfb8aa3b, v76
	v_mul_f32_e32 v83, 0xbfb8aa3b, v77
	v_exp_f32_e32 v82, v82
	v_exp_f32_e32 v83, v83
	v_mad_i64_i32 v[80:81], s[4:5], v174, s11, v[132:133]
	v_add_f32_e32 v82, 1.0, v82
	v_add_f32_e32 v83, 1.0, v83
	v_rcp_f32_e32 v82, v82
	v_rcp_f32_e32 v83, v83
	s_nop 0
	v_pk_mul_f32 v[76:77], v[76:77], v[82:83]
	s_nop 0
	v_pk_mul_f32 v[72:73], v[72:73], v[76:77]
	v_pk_mul_f32 v[76:77], v[78:79], v[154:155] op_sel_hi:[1,0]
	s_nop 0
	v_mul_f32_e32 v78, 0xbfb8aa3b, v76
	v_mul_f32_e32 v79, 0xbfb8aa3b, v77
	v_exp_f32_e32 v78, v78
	v_exp_f32_e32 v79, v79
	v_add_f32_e32 v78, 1.0, v78
	v_add_f32_e32 v79, 1.0, v79
	v_rcp_f32_e32 v78, v78
	v_rcp_f32_e32 v79, v79
	s_nop 0
	v_pk_mul_f32 v[76:77], v[76:77], v[78:79]
	s_nop 0
	v_pk_mul_f32 v[74:75], v[74:75], v[76:77]
	v_mul_f32_e32 v76, 0xbfb8aa3b, v68
	v_mul_f32_e32 v77, 0xbfb8aa3b, v69
	v_exp_f32_e32 v76, v76
	v_exp_f32_e32 v77, v77
	v_add_f32_e32 v76, 1.0, v76
	v_add_f32_e32 v77, 1.0, v77
	v_rcp_f32_e32 v76, v76
	v_rcp_f32_e32 v77, v77
	s_nop 0
	v_pk_mul_f32 v[68:69], v[68:69], v[76:77]
	s_nop 0
	v_pk_mul_f32 v[68:69], v[64:65], v[68:69]
	v_pk_mul_f32 v[64:65], v[70:71], v[154:155] op_sel_hi:[1,0]
	v_lshl_add_u64 v[76:77], v[80:81], 0, v[112:113]
	v_mul_f32_e32 v70, 0xbfb8aa3b, v64
	v_mul_f32_e32 v71, 0xbfb8aa3b, v65
	v_exp_f32_e32 v70, v70
	v_exp_f32_e32 v71, v71
	v_add_f32_e32 v70, 1.0, v70
	v_add_f32_e32 v71, 1.0, v71
	v_rcp_f32_e32 v70, v70
	v_rcp_f32_e32 v71, v71
	s_nop 0
	v_pk_mul_f32 v[64:65], v[64:65], v[70:71]
	s_nop 0
	v_pk_mul_f32 v[70:71], v[66:67], v[64:65]
	v_cvt_pk_bf16_f32 v64, v72, v73
	v_cvt_pk_bf16_f32 v65, v74, v75
	v_cvt_pk_bf16_f32 v66, v68, v69
	v_cvt_pk_bf16_f32 v67, v70, v71
	global_store_dwordx4 v[76:77], v[64:67], off
	s_nop 1
	v_mul_f32_e32 v66, 0xbfb8aa3b, v60
	v_mul_f32_e32 v67, 0xbfb8aa3b, v61
	v_exp_f32_e32 v66, v66
	v_exp_f32_e32 v67, v67
	v_mad_i64_i32 v[64:65], s[4:5], v158, s11, v[132:133]
	v_add_f32_e32 v66, 1.0, v66
	v_add_f32_e32 v67, 1.0, v67
	v_rcp_f32_e32 v66, v66
	v_rcp_f32_e32 v67, v67
	s_nop 0
	v_pk_mul_f32 v[60:61], v[60:61], v[66:67]
	s_nop 0
	v_pk_mul_f32 v[56:57], v[56:57], v[60:61]
	v_pk_mul_f32 v[60:61], v[62:63], v[156:157] op_sel_hi:[1,0]
	s_nop 0
	v_mul_f32_e32 v62, 0xbfb8aa3b, v60
	v_mul_f32_e32 v63, 0xbfb8aa3b, v61
	v_exp_f32_e32 v62, v62
	v_exp_f32_e32 v63, v63
	v_add_f32_e32 v62, 1.0, v62
	v_add_f32_e32 v63, 1.0, v63
	v_rcp_f32_e32 v62, v62
	v_rcp_f32_e32 v63, v63
	s_nop 0
	v_pk_mul_f32 v[60:61], v[60:61], v[62:63]
	s_nop 0
	v_pk_mul_f32 v[58:59], v[58:59], v[60:61]
	v_mul_f32_e32 v60, 0xbfb8aa3b, v52
	v_mul_f32_e32 v61, 0xbfb8aa3b, v53
	v_exp_f32_e32 v60, v60
	v_exp_f32_e32 v61, v61
	v_add_f32_e32 v60, 1.0, v60
	v_add_f32_e32 v61, 1.0, v61
	v_rcp_f32_e32 v60, v60
	v_rcp_f32_e32 v61, v61
	s_nop 0
	v_pk_mul_f32 v[52:53], v[52:53], v[60:61]
	s_nop 0
	v_pk_mul_f32 v[52:53], v[48:49], v[52:53]
	v_pk_mul_f32 v[48:49], v[54:55], v[156:157] op_sel_hi:[1,0]
	v_lshl_add_u64 v[60:61], v[64:65], 0, v[112:113]
	v_mul_f32_e32 v54, 0xbfb8aa3b, v48
	v_mul_f32_e32 v55, 0xbfb8aa3b, v49
	v_exp_f32_e32 v54, v54
	v_exp_f32_e32 v55, v55
	v_add_f32_e32 v54, 1.0, v54
	v_add_f32_e32 v55, 1.0, v55
	v_rcp_f32_e32 v54, v54
	v_rcp_f32_e32 v55, v55
	s_nop 0
	v_pk_mul_f32 v[48:49], v[48:49], v[54:55]
	s_nop 0
	v_pk_mul_f32 v[54:55], v[50:51], v[48:49]
	v_cvt_pk_bf16_f32 v48, v56, v57
	v_cvt_pk_bf16_f32 v49, v58, v59
	v_cvt_pk_bf16_f32 v50, v52, v53
	v_cvt_pk_bf16_f32 v51, v54, v55
	global_store_dwordx4 v[60:61], v[48:51], off
	s_nop 1
	v_mul_f32_e32 v50, 0xbfb8aa3b, v44
	v_mul_f32_e32 v51, 0xbfb8aa3b, v45
	v_exp_f32_e32 v50, v50
	v_exp_f32_e32 v51, v51
	v_mad_i64_i32 v[48:49], s[4:5], v152, s11, v[132:133]
; DEV float siluf(float x) { return x * __builtin_amdgcn_rcpf(1.0f + __builtin_amdgcn_exp2f(x * -1.4426950408889634f)); }
; DEV bf16x8 pack8(f32x4 a, f32x4 b) { u32x4 w; w.x = cvt_pk_bf16(a[0], a[1]); w.y = cvt_pk_bf16(a[2], a[3]); w.z = cvt_pk_bf16(b[0], b[1]); w.w = cvt_pk_bf16(b[2], b[3]); return __builtin_bit_cast(bf16x8, w); }
; #define PG8_WAIT_V(n) asm volatile("s_waitcnt vmcnt(" #n ")" ::: "memory")
; #define PG8_BAR __builtin_amdgcn_s_barrier()
; template <class Epi>
; DEV void gemm_phase(LAS unsigned char* lds, const Gemm g, const StaticOrder& S, const Epi& E) {
;     ...
;         if (!has_next) break;
; #pragma unroll
;         for (int a = 0; a < 2; ++a)
; #pragma unroll
;             for (int b = 0; b < 2; ++b)
; #pragma unroll
;                 for (int m = 0; m < 4; ++m)
; #pragma unroll
;                     for (int n = 0; n < 2; ++n) acc[a][b][m][n] = (f32x4){0.f, 0.f, 0.f, 0.f};
;         cur = nxt; cA = nA; cB = nB; ++ui;
;     }
;     PG8_WAIT_V(0);
;     if (wr == 0) PG8_BAR;
;     PG8_BAR;
;     DEV void operator()(AccRef acc, const pg8::Unit& u, int wr, int wc, int fr, int fq) const {
;     ...
;             for (int m = 0; m < 4; ++m) { u16* rowp = O + (size_t)(row0 + ai * 128 + m * 16) * 5632 + col0; const float rs = rsv[ai][m]; f32x4 r[2];
; #pragma unroll
;                 for (int n = 0; n < 2; ++n) { const f32x4 g = acc[ai][0][m][n] * rs, uu = acc[ai][1][m][n] * rs;
; #pragma unroll
;                     for (int e = 0; e < 4; ++e) r[n][e] = siluf(g[e]) * uu[e]; }
;                 *(u32x4*)rowp = __builtin_bit_cast(u32x4, pack8(r[0], r[1])); }
	v_add_f32_e32 v50, 1.0, v50
	v_add_f32_e32 v51, 1.0, v51
	v_rcp_f32_e32 v50, v50
	v_rcp_f32_e32 v51, v51
	s_nop 0
	v_pk_mul_f32 v[44:45], v[44:45], v[50:51]
	s_nop 0
	v_pk_mul_f32 v[40:41], v[40:41], v[44:45]
	v_pk_mul_f32 v[44:45], v[46:47], v[148:149] op_sel_hi:[1,0]
	s_nop 0
	v_mul_f32_e32 v46, 0xbfb8aa3b, v44
	v_mul_f32_e32 v47, 0xbfb8aa3b, v45
	v_exp_f32_e32 v46, v46
	v_exp_f32_e32 v47, v47
	v_add_f32_e32 v46, 1.0, v46
	v_add_f32_e32 v47, 1.0, v47
	v_rcp_f32_e32 v46, v46
	v_rcp_f32_e32 v47, v47
	s_nop 0
	v_pk_mul_f32 v[44:45], v[44:45], v[46:47]
	s_nop 0
	v_pk_mul_f32 v[42:43], v[42:43], v[44:45]
	v_mul_f32_e32 v44, 0xbfb8aa3b, v36
	v_mul_f32_e32 v45, 0xbfb8aa3b, v37
	v_exp_f32_e32 v44, v44
	v_exp_f32_e32 v45, v45
	v_add_f32_e32 v44, 1.0, v44
	v_add_f32_e32 v45, 1.0, v45
	v_rcp_f32_e32 v44, v44
	v_rcp_f32_e32 v45, v45
	s_nop 0
	v_pk_mul_f32 v[36:37], v[36:37], v[44:45]
	s_nop 0
	v_pk_mul_f32 v[36:37], v[32:33], v[36:37]
	v_pk_mul_f32 v[32:33], v[38:39], v[148:149] op_sel_hi:[1,0]
	v_lshl_add_u64 v[44:45], v[48:49], 0, v[112:113]
	v_mul_f32_e32 v38, 0xbfb8aa3b, v32
	v_mul_f32_e32 v39, 0xbfb8aa3b, v33
	v_exp_f32_e32 v38, v38
	v_exp_f32_e32 v39, v39
	v_add_f32_e32 v38, 1.0, v38
	v_add_f32_e32 v39, 1.0, v39
	v_rcp_f32_e32 v38, v38
	v_rcp_f32_e32 v39, v39
	s_nop 0
	v_pk_mul_f32 v[32:33], v[32:33], v[38:39]
	s_nop 0
	v_pk_mul_f32 v[38:39], v[34:35], v[32:33]
	v_cvt_pk_bf16_f32 v32, v40, v41
	v_cvt_pk_bf16_f32 v33, v42, v43
	v_cvt_pk_bf16_f32 v34, v36, v37
	v_cvt_pk_bf16_f32 v35, v38, v39
	global_store_dwordx4 v[44:45], v[32:35], off
	s_nop 1
	v_mul_f32_e32 v34, 0xbfb8aa3b, v28
	v_mul_f32_e32 v35, 0xbfb8aa3b, v29
	v_exp_f32_e32 v34, v34
	v_exp_f32_e32 v35, v35
	v_mad_i64_i32 v[32:33], s[4:5], v150, s11, v[132:133]
	v_add_f32_e32 v34, 1.0, v34
	v_add_f32_e32 v35, 1.0, v35
	v_rcp_f32_e32 v34, v34
	v_rcp_f32_e32 v35, v35
	s_nop 0
	v_pk_mul_f32 v[28:29], v[28:29], v[34:35]
	s_nop 0
	v_pk_mul_f32 v[24:25], v[24:25], v[28:29]
	v_pk_mul_f32 v[28:29], v[30:31], v[130:131] op_sel_hi:[1,0]
	s_nop 0
	v_mul_f32_e32 v30, 0xbfb8aa3b, v28
	v_mul_f32_e32 v31, 0xbfb8aa3b, v29
	v_exp_f32_e32 v30, v30
	v_exp_f32_e32 v31, v31
	v_add_f32_e32 v30, 1.0, v30
	v_add_f32_e32 v31, 1.0, v31
	v_rcp_f32_e32 v30, v30
	v_rcp_f32_e32 v31, v31
	s_nop 0
	v_pk_mul_f32 v[28:29], v[28:29], v[30:31]
	s_nop 0
	v_pk_mul_f32 v[26:27], v[26:27], v[28:29]
	v_mul_f32_e32 v28, 0xbfb8aa3b, v20
	v_mul_f32_e32 v29, 0xbfb8aa3b, v21
	v_exp_f32_e32 v28, v28
	v_exp_f32_e32 v29, v29
	v_add_f32_e32 v28, 1.0, v28
	v_add_f32_e32 v29, 1.0, v29
	v_rcp_f32_e32 v28, v28
	v_rcp_f32_e32 v29, v29
	s_nop 0
	v_pk_mul_f32 v[20:21], v[20:21], v[28:29]
	s_nop 0
	v_pk_mul_f32 v[20:21], v[16:17], v[20:21]
	v_pk_mul_f32 v[16:17], v[22:23], v[130:131] op_sel_hi:[1,0]
	v_lshl_add_u64 v[28:29], v[32:33], 0, v[112:113]
	v_mul_f32_e32 v22, 0xbfb8aa3b, v16
	v_mul_f32_e32 v23, 0xbfb8aa3b, v17
	v_exp_f32_e32 v22, v22
	v_exp_f32_e32 v23, v23
	v_add_f32_e32 v22, 1.0, v22
	v_add_f32_e32 v23, 1.0, v23
	v_rcp_f32_e32 v22, v22
	v_rcp_f32_e32 v23, v23
	s_nop 0
	v_pk_mul_f32 v[16:17], v[16:17], v[22:23]
	s_nop 0
	v_pk_mul_f32 v[22:23], v[18:19], v[16:17]
	v_cvt_pk_bf16_f32 v16, v24, v25
	v_cvt_pk_bf16_f32 v17, v26, v27
	v_cvt_pk_bf16_f32 v18, v20, v21
	v_cvt_pk_bf16_f32 v19, v22, v23
	global_store_dwordx4 v[28:29], v[16:19], off
	s_nop 1
	v_mul_f32_e32 v18, 0xbfb8aa3b, v12
	v_mul_f32_e32 v19, 0xbfb8aa3b, v13
	v_exp_f32_e32 v18, v18
	v_exp_f32_e32 v19, v19
	v_mad_i64_i32 v[16:17], s[4:5], v146, s11, v[132:133]
	v_add_f32_e32 v18, 1.0, v18
	v_add_f32_e32 v19, 1.0, v19
	v_rcp_f32_e32 v18, v18
	v_rcp_f32_e32 v19, v19
	s_mov_b32 s4, s14
	v_pk_mul_f32 v[12:13], v[12:13], v[18:19]
	s_nop 0
	v_pk_mul_f32 v[8:9], v[8:9], v[12:13]
	v_pk_mul_f32 v[12:13], v[14:15], v[128:129] op_sel_hi:[1,0]
	s_nop 0
	v_mul_f32_e32 v14, 0xbfb8aa3b, v12
	v_mul_f32_e32 v15, 0xbfb8aa3b, v13
	v_exp_f32_e32 v14, v14
	v_exp_f32_e32 v15, v15
	v_add_f32_e32 v14, 1.0, v14
	v_add_f32_e32 v15, 1.0, v15
	v_rcp_f32_e32 v14, v14
	v_rcp_f32_e32 v15, v15
	s_nop 0
	v_pk_mul_f32 v[12:13], v[12:13], v[14:15]
	s_nop 0
	v_pk_mul_f32 v[10:11], v[10:11], v[12:13]
	v_mul_f32_e32 v12, 0xbfb8aa3b, v4
	v_mul_f32_e32 v13, 0xbfb8aa3b, v5
	v_exp_f32_e32 v12, v12
	v_exp_f32_e32 v13, v13
	v_add_f32_e32 v12, 1.0, v12
	v_add_f32_e32 v13, 1.0, v13
	v_rcp_f32_e32 v12, v12
	v_rcp_f32_e32 v13, v13
	s_nop 0
	v_pk_mul_f32 v[4:5], v[4:5], v[12:13]
	s_nop 0
	v_pk_mul_f32 v[4:5], v[0:1], v[4:5]
	v_pk_mul_f32 v[0:1], v[6:7], v[128:129] op_sel_hi:[1,0]
	v_lshl_add_u64 v[12:13], v[16:17], 0, v[112:113]
	v_mul_f32_e32 v6, 0xbfb8aa3b, v0
	v_mul_f32_e32 v7, 0xbfb8aa3b, v1
	v_exp_f32_e32 v6, v6
	v_exp_f32_e32 v7, v7
	v_add_f32_e32 v6, 1.0, v6
	v_add_f32_e32 v7, 1.0, v7
	v_rcp_f32_e32 v6, v6
	v_rcp_f32_e32 v7, v7
	s_nop 0
	v_pk_mul_f32 v[0:1], v[0:1], v[6:7]
	s_nop 0
	v_pk_mul_f32 v[6:7], v[2:3], v[0:1]
	v_cvt_pk_bf16_f32 v0, v8, v9
	v_cvt_pk_bf16_f32 v1, v10, v11
	v_cvt_pk_bf16_f32 v2, v4, v5
	v_cvt_pk_bf16_f32 v3, v6, v7
	global_store_dwordx4 v[12:13], v[0:3], off
	s_cbranch_vccz .LBB0_752
	s_waitcnt vmcnt(0)
	s_cmpk_gt_u32 s27, 0xff
	s_cbranch_scc1 .LBB0_759
	s_barrier
